# xpv
# baseline (speedup 1.0000x reference)
; __device__ __forceinline__ void xattn_item(const Params& p, char* smem, const int tile, const int hm) {
;     ...
;     const int tok0 = tile * 64;
;     const int b = tok0 >> 13;
;     __syncthreads();
; #pragma unroll
;     for (int i = 0; i < 8; ++i) {
;       const int c = tid + 256 * i, row = c >> 5, cc = c & 31;
;       *(uint4*)(sQ + row * 264 + cc * 8) = *(const uint4*)(qm + (size_t)(tok0 + row) * 1024 + hm * 256 + cc * 8);
;     }
;     f32x4 acc[4][4];
;     u32x4 st[8];
; #pragma unroll
;     for (int m = 0; m < 4; ++m)
; #pragma unroll
;       for (int n = 0; n < 4; ++n) acc[m][n] = f32x4{0.f, 0.f, 0.f, 0.f};
;     for (int kt = 0; kt < 4; ++kt) {
; #pragma unroll
;       for (int i = 0; i < 8; ++i) {
;         const int c = tid + 256 * i, row = c >> 3, cc = c & 7;
;         st[i] = *(const u32x4*)(kmem + (size_t)(b * 256 + row) * 1024 + hm * 256 + kt * 64 + cc * 8);
;       }
;       __syncthreads();
; #pragma unroll
;       for (int i = 0; i < 8; ++i) {
;         const int c = tid + 256 * i, row = c >> 3, cc = c & 7;
;         *(u32x4*)(sT + row * 72 + cc * 8) = st[i];
;       }
;       __syncthreads();
.LBB0_366:
	s_and_b64 vcc, exec, s[4:5]
	s_cbranch_vccz .LBB0_432
	s_lshl_b32 s4, s93, 1
	s_lshr_b32 s5, s94, 2
	s_add_i32 s42, s4, s5
	s_lshl_b32 s4, s94, 8
	s_and_b32 s41, s4, 0x300
	v_mov_b32_e32 v16, v197
	s_lshl_b32 s6, s42, 6
	s_lshl_b32 s40, s41, 1
	s_add_u32 s4, s12, s40
	v_lshlrev_b32_e32 v0, 4, v16
	v_add_u32_e32 v7, 0x100, v16
	s_addc_u32 s5, s13, 0
	v_and_b32_e32 v100, 0x1f0, v0
	v_ashrrev_i32_e32 v4, 5, v16
	v_ashrrev_i32_e32 v8, 5, v7
	v_lshl_add_u64 v[0:1], s[4:5], 0, v[100:101]
	v_add_u32_e32 v2, s6, v4
	s_waitcnt vmcnt(20)
	v_mad_u64_u32 v[62:63], s[4:5], v4, s81, v[100:101]
	v_add_u32_e32 v4, s6, v8
	v_ashrrev_i32_e32 v3, 31, v2
	v_ashrrev_i32_e32 v5, 31, v4
	v_lshlrev_b64 v[2:3], 11, v[2:3]
	v_lshlrev_b64 v[4:5], 11, v[4:5]
	v_lshl_add_u64 v[2:3], v[0:1], 0, v[2:3]
	v_lshl_add_u64 v[4:5], v[0:1], 0, v[4:5]
	s_waitcnt vmcnt(19)
	v_mad_u64_u32 v[64:65], s[4:5], v8, s81, v[100:101]
	v_add_u32_e32 v8, 0x200, v16
	v_add_u32_e32 v9, 0x300, v16
	s_barrier
	global_load_dwordx4 v[18:21], v[2:3], off
	global_load_dwordx4 v[22:25], v[4:5], off
	v_ashrrev_i32_e32 v4, 5, v8
	v_ashrrev_i32_e32 v10, 5, v9
	v_add_u32_e32 v2, s6, v4
	v_mad_u64_u32 v[94:95], s[4:5], v4, s81, v[100:101]
	v_add_u32_e32 v4, s6, v10
	v_ashrrev_i32_e32 v3, 31, v2
	v_ashrrev_i32_e32 v5, 31, v4
	v_lshlrev_b64 v[2:3], 11, v[2:3]
	v_lshlrev_b64 v[4:5], 11, v[4:5]
	v_lshl_add_u64 v[2:3], v[0:1], 0, v[2:3]
	v_lshl_add_u64 v[4:5], v[0:1], 0, v[4:5]
	v_mad_u64_u32 v[96:97], s[4:5], v10, s81, v[100:101]
	v_add_u32_e32 v10, 0x400, v16
	v_add_u32_e32 v11, 0x500, v16
	global_load_dwordx4 v[26:29], v[2:3], off
	global_load_dwordx4 v[30:33], v[4:5], off
	v_ashrrev_i32_e32 v4, 5, v10
	v_ashrrev_i32_e32 v12, 5, v11
	v_add_u32_e32 v2, s6, v4
	v_mad_u64_u32 v[98:99], s[4:5], v4, s81, v[100:101]
	v_add_u32_e32 v4, s6, v12
	v_ashrrev_i32_e32 v3, 31, v2
	v_ashrrev_i32_e32 v5, 31, v4
	v_lshlrev_b64 v[2:3], 11, v[2:3]
	v_lshlrev_b64 v[4:5], 11, v[4:5]
	v_lshl_add_u64 v[2:3], v[0:1], 0, v[2:3]
	v_lshl_add_u64 v[4:5], v[0:1], 0, v[4:5]
	v_mad_u64_u32 v[104:105], s[4:5], v12, s81, v[100:101]
	v_add_u32_e32 v12, 0x600, v16
	global_load_dwordx4 v[34:37], v[2:3], off
	global_load_dwordx4 v[38:41], v[4:5], off
	v_ashrrev_i32_e32 v4, 5, v12
	v_add_u32_e32 v17, 0x700, v16
	v_add_u32_e32 v2, s6, v4
	v_ashrrev_i32_e32 v13, 5, v17
	v_ashrrev_i32_e32 v3, 31, v2
	v_mad_u64_u32 v[106:107], s[4:5], v4, s81, v[100:101]
	v_add_u32_e32 v4, s6, v13
	v_lshlrev_b64 v[2:3], 11, v[2:3]
	v_ashrrev_i32_e32 v5, 31, v4
	v_lshl_add_u64 v[2:3], v[0:1], 0, v[2:3]
	v_lshlrev_b64 v[4:5], 11, v[4:5]
	v_lshl_add_u64 v[0:1], v[0:1], 0, v[4:5]
	global_load_dwordx4 v[42:45], v[2:3], off
	global_load_dwordx4 v[46:49], v[0:1], off
	v_lshlrev_b32_e32 v6, 3, v16
	s_ashr_i32 s42, s42, 7
	v_mad_u64_u32 v[108:109], s[4:5], v13, s81, v[100:101]
	s_lshl_b32 s43, s42, 8
	v_and_b32_e32 v0, 56, v6
	v_ashrrev_i32_e32 v65, 3, v16
	v_ashrrev_i32_e32 v66, 3, v7
	v_ashrrev_i32_e32 v67, 3, v8
	s_waitcnt vmcnt(26)
	v_ashrrev_i32_e32 v68, 3, v9
	v_ashrrev_i32_e32 v69, 3, v10
	v_ashrrev_i32_e32 v70, 3, v11
	v_ashrrev_i32_e32 v71, 3, v12
	v_ashrrev_i32_e32 v72, 3, v17
	s_add_u32 s4, s52, s40
	v_lshlrev_b32_e32 v100, 1, v0
	v_add_u32_e32 v0, s43, v65
	v_add_u32_e32 v2, s43, v66
	v_add_u32_e32 v4, s43, v67
	v_add_u32_e32 v6, s43, v68
	v_add_u32_e32 v8, s43, v69
	v_add_u32_e32 v10, s43, v70
	v_add_u32_e32 v12, s43, v71
	v_add_u32_e32 v90, s43, v72
	s_addc_u32 s5, s53, 0
	v_ashrrev_i32_e32 v1, 31, v0
	v_ashrrev_i32_e32 v3, 31, v2
	v_ashrrev_i32_e32 v5, 31, v4
	v_ashrrev_i32_e32 v7, 31, v6
	v_ashrrev_i32_e32 v9, 31, v8
	v_ashrrev_i32_e32 v11, 31, v10
	v_ashrrev_i32_e32 v13, 31, v12
	v_ashrrev_i32_e32 v91, 31, v90
	v_lshl_add_u64 v[14:15], s[4:5], 0, v[100:101]
	v_lshlrev_b64 v[0:1], 11, v[0:1]
	v_lshlrev_b64 v[2:3], 11, v[2:3]
	v_lshlrev_b64 v[4:5], 11, v[4:5]
	v_lshlrev_b64 v[6:7], 11, v[6:7]
	v_lshlrev_b64 v[8:9], 11, v[8:9]
	v_lshlrev_b64 v[10:11], 11, v[10:11]
	v_lshlrev_b64 v[12:13], 11, v[12:13]
	v_lshlrev_b64 v[90:91], 11, v[90:91]
	v_lshl_add_u64 v[0:1], v[14:15], 0, v[0:1]
	v_lshl_add_u64 v[2:3], v[14:15], 0, v[2:3]
	v_lshl_add_u64 v[4:5], v[14:15], 0, v[4:5]
	v_lshl_add_u64 v[6:7], v[14:15], 0, v[6:7]
	v_lshl_add_u64 v[8:9], v[14:15], 0, v[8:9]
	v_lshl_add_u64 v[10:11], v[14:15], 0, v[10:11]
	v_lshl_add_u64 v[12:13], v[14:15], 0, v[12:13]
	v_lshl_add_u64 v[14:15], v[14:15], 0, v[90:91]
	global_load_dwordx4 v[50:53], v[0:1], off
	global_load_dwordx4 v[54:57], v[2:3], off
	global_load_dwordx4 v[58:61], v[4:5], off
	global_load_dwordx4 v[74:77], v[6:7], off
	global_load_dwordx4 v[78:81], v[8:9], off
	global_load_dwordx4 v[82:85], v[10:11], off
	global_load_dwordx4 v[86:89], v[12:13], off
	global_load_dwordx4 v[90:93], v[14:15], off
	v_mul_lo_u32 v17, v65, s82
	s_waitcnt vmcnt(15)
	ds_write_b128 v62, v[18:21]
	s_waitcnt vmcnt(14)
	ds_write_b128 v64, v[22:25]
	s_waitcnt vmcnt(13)
	ds_write_b128 v94, v[26:29]
	s_waitcnt vmcnt(12)
	ds_write_b128 v96, v[30:33]
	s_waitcnt vmcnt(11)
	ds_write_b128 v98, v[34:37]
	s_waitcnt vmcnt(10)
	ds_write_b128 v104, v[38:41]
	s_waitcnt vmcnt(9)
	ds_write_b128 v106, v[42:45]
	s_waitcnt vmcnt(8)
	ds_write_b128 v108, v[46:49]
	v_add_u32_e32 v98, v100, v17
	v_mul_lo_u32 v17, v66, s82
	v_add_u32_e32 v99, v100, v17
	v_mul_lo_u32 v17, v67, s82
	v_add_u32_e32 v104, v100, v17
	v_mul_lo_u32 v17, v68, s82
	v_add_u32_e32 v105, v100, v17
	v_mul_lo_u32 v17, v69, s82
	v_add_u32_e32 v106, v100, v17
	v_mul_lo_u32 v17, v70, s82
	v_bfe_u32 v73, v16, 4, 2
	v_add_u32_e32 v108, v100, v17
	v_mul_lo_u32 v17, v71, s82
	v_and_b32_e32 v112, 15, v16
	v_lshlrev_b32_e32 v64, 4, v73
	v_add_u32_e32 v109, v100, v17
	v_mul_lo_u32 v17, v72, s82
	v_add_u32_e32 v110, v100, v17
	v_mad_u32_u24 v17, v112, s81, v64
	s_waitcnt lgkmcnt(0)
	s_barrier
; #define MFMA(a, b, c) __builtin_amdgcn_mfma_f32_16x16x32_bf16((a), (b), (c), 0, 0, 0)
; __device__ __forceinline__ void xattn_item(const Params& p, char* smem, const int tile, const int hm) {
;     ...
;     for (int kt = 0; kt < 4; ++kt) {
; #pragma unroll
;       for (int i = 0; i < 8; ++i) {
;         const int c = tid + 256 * i, row = c >> 3, cc = c & 7;
;         st[i] = *(const u32x4*)(kmem + (size_t)(b * 256 + row) * 1024 + hm * 256 + kt * 64 + cc * 8);
;       }
;       __syncthreads();
; #pragma unroll
;       for (int i = 0; i < 8; ++i) {
;         const int c = tid + 256 * i, row = c >> 3, cc = c & 7;
;         *(u32x4*)(sT + row * 72 + cc * 8) = st[i];
;       }
;       __syncthreads();
; #pragma unroll
;       for (int ks = 0; ks < 2; ++ks) {
;         bf16x8 af[4], bfr[4];
; #pragma unroll
;         for (int m = 0; m < 4; ++m) af[m] = *(const bf16x8*)(sQ + (m * 16 + l15) * 264 + kt * 64 + ks * 32 + lq * 8);
; #pragma unroll
;         for (int n = 0; n < 4; ++n) bfr[n] = *(const bf16x8*)(sT + (w * 64 + n * 16 + l15) * 72 + ks * 32 + lq * 8);
; #pragma unroll
;         for (int m = 0; m < 4; ++m)
; #pragma unroll
;           for (int n = 0; n < 4; ++n) acc[m][n] = MFMA(af[m], bfr[n], acc[m][n]);
;       }
	v_and_b32_e32 v22, 0xfffffcf, v16
	v_mul_lo_u32 v22, v22, s82
	v_add_u32_e32 v107, v64, v22
	v_cmp_eq_u32_e32 vcc, 0, v112
	s_waitcnt vmcnt(7)
	ds_write_b128 v98, v[50:53] offset:33792
	s_waitcnt vmcnt(6)
	ds_write_b128 v99, v[54:57] offset:33792
	s_waitcnt vmcnt(5)
	ds_write_b128 v104, v[58:61] offset:33792
	s_waitcnt vmcnt(4)
	ds_write_b128 v105, v[74:77] offset:33792
	s_waitcnt vmcnt(3)
	ds_write_b128 v106, v[78:81] offset:33792
	s_waitcnt vmcnt(2)
	ds_write_b128 v108, v[82:85] offset:33792
	s_waitcnt vmcnt(1)
	ds_write_b128 v109, v[86:89] offset:33792
	s_waitcnt vmcnt(0)
	ds_write_b128 v110, v[90:93] offset:33792
	s_waitcnt lgkmcnt(0)
	s_barrier
	v_or_b32_e32 v54, 48, v16
	v_mul_lo_u32 v54, v54, s82
	v_add_u32_e32 v111, v64, v54
	v_lshrrev_b32_e32 v254, 6, v197
	v_and_b32_e32 v255, 15, v197
	v_lshl_add_u32 v254, v254, 6, v255
	v_bfe_u32 v255, v197, 4, 2
	v_lshlrev_b32_e32 v254, 11, v254
	v_lshl_add_u32 v252, v255, 4, v254
	v_add_u32_e32 v253, 0x10000, v252
	s_lshl_b32 s100, s43, 11
	s_add_u32 s96, s52, s40
	s_addc_u32 s97, s53, 0
	s_add_u32 s96, s96, s100
	s_addc_u32 s97, s97, 0
	s_add_u32 s98, s96, 0x8000
	s_addc_u32 s99, s97, 0
	global_load_dwordx4 v[210:213], v252, s[96:97]
	global_load_dwordx4 v[214:217], v252, s[96:97] offset:64
	global_load_dwordx4 v[218:221], v252, s[98:99]
	global_load_dwordx4 v[222:225], v252, s[98:99] offset:64
	global_load_dwordx4 v[226:229], v253, s[96:97]
	global_load_dwordx4 v[230:233], v253, s[96:97] offset:64
	global_load_dwordx4 v[234:237], v253, s[98:99]
	global_load_dwordx4 v[238:241], v253, s[98:99] offset:64
	global_load_dwordx4 v[74:77], v252, s[96:97] offset:128
	global_load_dwordx4 v[78:81], v252, s[96:97] offset:192
	global_load_dwordx4 v[82:85], v252, s[98:99] offset:128
	global_load_dwordx4 v[86:89], v252, s[98:99] offset:192
	global_load_dwordx4 v[90:93], v253, s[96:97] offset:128
	global_load_dwordx4 v[94:97], v253, s[96:97] offset:192
	global_load_dwordx4 v[172:175], v253, s[98:99] offset:128
	global_load_dwordx4 v[176:179], v253, s[98:99] offset:192
	ds_read_b128 v[140:143], v17
	ds_read_b128 v[144:147], v17 offset:8448
	ds_read_b128 v[148:151], v17 offset:16896
	ds_read_b128 v[152:155], v17 offset:25344
	ds_read_b128 v[156:159], v17 offset:64
	ds_read_b128 v[160:163], v17 offset:8512
	ds_read_b128 v[164:167], v17 offset:16960
	ds_read_b128 v[168:171], v17 offset:25408
	s_waitcnt vmcnt(8)
	s_waitcnt lgkmcnt(4)
	v_mfma_f32_16x16x32_bf16 v[60:63], v[140:143], v[210:213], 0
	v_mfma_f32_16x16x32_bf16 v[56:59], v[140:143], v[218:221], 0
	v_mfma_f32_16x16x32_bf16 v[52:55], v[140:143], v[226:229], 0
	v_mfma_f32_16x16x32_bf16 v[48:51], v[140:143], v[234:237], 0
	v_mfma_f32_16x16x32_bf16 v[44:47], v[144:147], v[210:213], 0
	v_mfma_f32_16x16x32_bf16 v[40:43], v[144:147], v[218:221], 0
	v_mfma_f32_16x16x32_bf16 v[36:39], v[144:147], v[226:229], 0
	v_mfma_f32_16x16x32_bf16 v[32:35], v[144:147], v[234:237], 0
	v_mfma_f32_16x16x32_bf16 v[28:31], v[148:151], v[210:213], 0
	v_mfma_f32_16x16x32_bf16 v[24:27], v[148:151], v[218:221], 0
	v_mfma_f32_16x16x32_bf16 v[20:23], v[148:151], v[226:229], 0
	v_mfma_f32_16x16x32_bf16 v[244:247], v[148:151], v[234:237], 0
	v_mfma_f32_16x16x32_bf16 v[12:15], v[152:155], v[210:213], 0
	v_mfma_f32_16x16x32_bf16 v[8:11], v[152:155], v[218:221], 0
	v_mfma_f32_16x16x32_bf16 v[4:7], v[152:155], v[226:229], 0
	v_mfma_f32_16x16x32_bf16 v[248:251], v[152:155], v[234:237], 0
	ds_read_b128 v[140:143], v17 offset:128
	ds_read_b128 v[144:147], v17 offset:8576
	ds_read_b128 v[148:151], v17 offset:17024
	ds_read_b128 v[152:155], v17 offset:25472
	s_waitcnt lgkmcnt(4)
	v_mfma_f32_16x16x32_bf16 v[60:63], v[156:159], v[214:217], v[60:63]
	v_mfma_f32_16x16x32_bf16 v[56:59], v[156:159], v[222:225], v[56:59]
	v_mfma_f32_16x16x32_bf16 v[52:55], v[156:159], v[230:233], v[52:55]
	v_mfma_f32_16x16x32_bf16 v[48:51], v[156:159], v[238:241], v[48:51]
	v_mfma_f32_16x16x32_bf16 v[44:47], v[160:163], v[214:217], v[44:47]
	v_mfma_f32_16x16x32_bf16 v[40:43], v[160:163], v[222:225], v[40:43]
	v_mfma_f32_16x16x32_bf16 v[36:39], v[160:163], v[230:233], v[36:39]
	v_mfma_f32_16x16x32_bf16 v[32:35], v[160:163], v[238:241], v[32:35]
	v_mfma_f32_16x16x32_bf16 v[28:31], v[164:167], v[214:217], v[28:31]
	v_mfma_f32_16x16x32_bf16 v[24:27], v[164:167], v[222:225], v[24:27]
	v_mfma_f32_16x16x32_bf16 v[20:23], v[164:167], v[230:233], v[20:23]
	v_mfma_f32_16x16x32_bf16 v[244:247], v[164:167], v[238:241], v[244:247]
	v_mfma_f32_16x16x32_bf16 v[12:15], v[168:171], v[214:217], v[12:15]
	v_mfma_f32_16x16x32_bf16 v[8:11], v[168:171], v[222:225], v[8:11]
	v_mfma_f32_16x16x32_bf16 v[4:7], v[168:171], v[230:233], v[4:7]
	v_mfma_f32_16x16x32_bf16 v[248:251], v[168:171], v[238:241], v[248:251]
	ds_read_b128 v[156:159], v17 offset:192
	ds_read_b128 v[160:163], v17 offset:8640
	ds_read_b128 v[164:167], v17 offset:17088
	ds_read_b128 v[168:171], v17 offset:25536
	global_load_dwordx4 v[210:213], v252, s[96:97] offset:256
	global_load_dwordx4 v[214:217], v252, s[96:97] offset:320
	global_load_dwordx4 v[218:221], v252, s[98:99] offset:256
	global_load_dwordx4 v[222:225], v252, s[98:99] offset:320
	global_load_dwordx4 v[226:229], v253, s[96:97] offset:256
	global_load_dwordx4 v[230:233], v253, s[96:97] offset:320
	global_load_dwordx4 v[234:237], v253, s[98:99] offset:256
	global_load_dwordx4 v[238:241], v253, s[98:99] offset:320
	s_waitcnt vmcnt(8)
	s_waitcnt lgkmcnt(4)
; #define MFMA(a, b, c) __builtin_amdgcn_mfma_f32_16x16x32_bf16((a), (b), (c), 0, 0, 0)
; __device__ __forceinline__ void xattn_item(const Params& p, char* smem, const int tile, const int hm) {
;     ...
;     for (int kt = 0; kt < 4; ++kt) {
; #pragma unroll
;       for (int i = 0; i < 8; ++i) {
;         const int c = tid + 256 * i, row = c >> 3, cc = c & 7;
;         st[i] = *(const u32x4*)(kmem + (size_t)(b * 256 + row) * 1024 + hm * 256 + kt * 64 + cc * 8);
;       }
;       __syncthreads();
; #pragma unroll
;       for (int i = 0; i < 8; ++i) {
;         const int c = tid + 256 * i, row = c >> 3, cc = c & 7;
;         *(u32x4*)(sT + row * 72 + cc * 8) = st[i];
;       }
;       __syncthreads();
; #pragma unroll
;       for (int ks = 0; ks < 2; ++ks) {
;         bf16x8 af[4], bfr[4];
; #pragma unroll
;         for (int m = 0; m < 4; ++m) af[m] = *(const bf16x8*)(sQ + (m * 16 + l15) * 264 + kt * 64 + ks * 32 + lq * 8);
; #pragma unroll
;         for (int n = 0; n < 4; ++n) bfr[n] = *(const bf16x8*)(sT + (w * 64 + n * 16 + l15) * 72 + ks * 32 + lq * 8);
; #pragma unroll
;         for (int m = 0; m < 4; ++m)
; #pragma unroll
;           for (int n = 0; n < 4; ++n) acc[m][n] = MFMA(af[m], bfr[n], acc[m][n]);
;       }
	v_mfma_f32_16x16x32_bf16 v[60:63], v[140:143], v[74:77], v[60:63]
	v_mfma_f32_16x16x32_bf16 v[56:59], v[140:143], v[82:85], v[56:59]
	v_mfma_f32_16x16x32_bf16 v[52:55], v[140:143], v[90:93], v[52:55]
	v_mfma_f32_16x16x32_bf16 v[48:51], v[140:143], v[172:175], v[48:51]
	v_mfma_f32_16x16x32_bf16 v[44:47], v[144:147], v[74:77], v[44:47]
	v_mfma_f32_16x16x32_bf16 v[40:43], v[144:147], v[82:85], v[40:43]
	v_mfma_f32_16x16x32_bf16 v[36:39], v[144:147], v[90:93], v[36:39]
	v_mfma_f32_16x16x32_bf16 v[32:35], v[144:147], v[172:175], v[32:35]
	v_mfma_f32_16x16x32_bf16 v[28:31], v[148:151], v[74:77], v[28:31]
	v_mfma_f32_16x16x32_bf16 v[24:27], v[148:151], v[82:85], v[24:27]
	v_mfma_f32_16x16x32_bf16 v[20:23], v[148:151], v[90:93], v[20:23]
	v_mfma_f32_16x16x32_bf16 v[244:247], v[148:151], v[172:175], v[244:247]
	v_mfma_f32_16x16x32_bf16 v[12:15], v[152:155], v[74:77], v[12:15]
	v_mfma_f32_16x16x32_bf16 v[8:11], v[152:155], v[82:85], v[8:11]
	v_mfma_f32_16x16x32_bf16 v[4:7], v[152:155], v[90:93], v[4:7]
	v_mfma_f32_16x16x32_bf16 v[248:251], v[152:155], v[172:175], v[248:251]
	ds_read_b128 v[140:143], v17 offset:256
	ds_read_b128 v[144:147], v17 offset:8704
	ds_read_b128 v[148:151], v17 offset:17152
	ds_read_b128 v[152:155], v17 offset:25600
	s_waitcnt lgkmcnt(4)
	v_mfma_f32_16x16x32_bf16 v[60:63], v[156:159], v[78:81], v[60:63]
	v_mfma_f32_16x16x32_bf16 v[56:59], v[156:159], v[86:89], v[56:59]
	v_mfma_f32_16x16x32_bf16 v[52:55], v[156:159], v[94:97], v[52:55]
	v_mfma_f32_16x16x32_bf16 v[48:51], v[156:159], v[176:179], v[48:51]
	v_mfma_f32_16x16x32_bf16 v[44:47], v[160:163], v[78:81], v[44:47]
	v_mfma_f32_16x16x32_bf16 v[40:43], v[160:163], v[86:89], v[40:43]
	v_mfma_f32_16x16x32_bf16 v[36:39], v[160:163], v[94:97], v[36:39]
	v_mfma_f32_16x16x32_bf16 v[32:35], v[160:163], v[176:179], v[32:35]
	v_mfma_f32_16x16x32_bf16 v[28:31], v[164:167], v[78:81], v[28:31]
	v_mfma_f32_16x16x32_bf16 v[24:27], v[164:167], v[86:89], v[24:27]
	v_mfma_f32_16x16x32_bf16 v[20:23], v[164:167], v[94:97], v[20:23]
	v_mfma_f32_16x16x32_bf16 v[244:247], v[164:167], v[176:179], v[244:247]
	v_mfma_f32_16x16x32_bf16 v[12:15], v[168:171], v[78:81], v[12:15]
	v_mfma_f32_16x16x32_bf16 v[8:11], v[168:171], v[86:89], v[8:11]
	v_mfma_f32_16x16x32_bf16 v[4:7], v[168:171], v[94:97], v[4:7]
	v_mfma_f32_16x16x32_bf16 v[248:251], v[168:171], v[176:179], v[248:251]
	ds_read_b128 v[156:159], v17 offset:320
	ds_read_b128 v[160:163], v17 offset:8768
	ds_read_b128 v[164:167], v17 offset:17216
	ds_read_b128 v[168:171], v17 offset:25664
	global_load_dwordx4 v[74:77], v252, s[96:97] offset:384
	global_load_dwordx4 v[78:81], v252, s[96:97] offset:448
	global_load_dwordx4 v[82:85], v252, s[98:99] offset:384
	global_load_dwordx4 v[86:89], v252, s[98:99] offset:448
	global_load_dwordx4 v[90:93], v253, s[96:97] offset:384
	global_load_dwordx4 v[94:97], v253, s[96:97] offset:448
	global_load_dwordx4 v[172:175], v253, s[98:99] offset:384
	global_load_dwordx4 v[176:179], v253, s[98:99] offset:448
	s_waitcnt vmcnt(8)
	s_waitcnt lgkmcnt(4)
	v_mfma_f32_16x16x32_bf16 v[60:63], v[140:143], v[210:213], v[60:63]
	v_mfma_f32_16x16x32_bf16 v[56:59], v[140:143], v[218:221], v[56:59]
	v_mfma_f32_16x16x32_bf16 v[52:55], v[140:143], v[226:229], v[52:55]
	v_mfma_f32_16x16x32_bf16 v[48:51], v[140:143], v[234:237], v[48:51]
	v_mfma_f32_16x16x32_bf16 v[44:47], v[144:147], v[210:213], v[44:47]
	v_mfma_f32_16x16x32_bf16 v[40:43], v[144:147], v[218:221], v[40:43]
	v_mfma_f32_16x16x32_bf16 v[36:39], v[144:147], v[226:229], v[36:39]
	v_mfma_f32_16x16x32_bf16 v[32:35], v[144:147], v[234:237], v[32:35]
	v_mfma_f32_16x16x32_bf16 v[28:31], v[148:151], v[210:213], v[28:31]
	v_mfma_f32_16x16x32_bf16 v[24:27], v[148:151], v[218:221], v[24:27]
	v_mfma_f32_16x16x32_bf16 v[20:23], v[148:151], v[226:229], v[20:23]
	v_mfma_f32_16x16x32_bf16 v[244:247], v[148:151], v[234:237], v[244:247]
	v_mfma_f32_16x16x32_bf16 v[12:15], v[152:155], v[210:213], v[12:15]
	v_mfma_f32_16x16x32_bf16 v[8:11], v[152:155], v[218:221], v[8:11]
	v_mfma_f32_16x16x32_bf16 v[4:7], v[152:155], v[226:229], v[4:7]
	v_mfma_f32_16x16x32_bf16 v[248:251], v[152:155], v[234:237], v[248:251]
	ds_read_b128 v[140:143], v17 offset:384
	ds_read_b128 v[144:147], v17 offset:8832
	ds_read_b128 v[148:151], v17 offset:17280
	ds_read_b128 v[152:155], v17 offset:25728
	s_waitcnt lgkmcnt(4)
	v_mfma_f32_16x16x32_bf16 v[60:63], v[156:159], v[214:217], v[60:63]
	v_mfma_f32_16x16x32_bf16 v[56:59], v[156:159], v[222:225], v[56:59]
	v_mfma_f32_16x16x32_bf16 v[52:55], v[156:159], v[230:233], v[52:55]
	v_mfma_f32_16x16x32_bf16 v[48:51], v[156:159], v[238:241], v[48:51]
	v_mfma_f32_16x16x32_bf16 v[44:47], v[160:163], v[214:217], v[44:47]
	v_mfma_f32_16x16x32_bf16 v[40:43], v[160:163], v[222:225], v[40:43]
	v_mfma_f32_16x16x32_bf16 v[36:39], v[160:163], v[230:233], v[36:39]
	v_mfma_f32_16x16x32_bf16 v[32:35], v[160:163], v[238:241], v[32:35]
	v_mfma_f32_16x16x32_bf16 v[28:31], v[164:167], v[214:217], v[28:31]
	v_mfma_f32_16x16x32_bf16 v[24:27], v[164:167], v[222:225], v[24:27]
	v_mfma_f32_16x16x32_bf16 v[20:23], v[164:167], v[230:233], v[20:23]
	v_mfma_f32_16x16x32_bf16 v[244:247], v[164:167], v[238:241], v[244:247]
	v_mfma_f32_16x16x32_bf16 v[12:15], v[168:171], v[214:217], v[12:15]
	v_mfma_f32_16x16x32_bf16 v[8:11], v[168:171], v[222:225], v[8:11]
	v_mfma_f32_16x16x32_bf16 v[4:7], v[168:171], v[230:233], v[4:7]
	v_mfma_f32_16x16x32_bf16 v[248:251], v[168:171], v[238:241], v[248:251]
	ds_read_b128 v[156:159], v17 offset:448
	ds_read_b128 v[160:163], v17 offset:8896
	ds_read_b128 v[164:167], v17 offset:17344
	ds_read_b128 v[168:171], v17 offset:25792
	s_waitcnt vmcnt(0)
	s_waitcnt lgkmcnt(4)
; #define MFMA(a, b, c) __builtin_amdgcn_mfma_f32_16x16x32_bf16((a), (b), (c), 0, 0, 0)
; __device__ __forceinline__ void xattn_item(const Params& p, char* smem, const int tile, const int hm) {
;     ...
;       for (int ks = 0; ks < 2; ++ks) {
;         bf16x8 af[4], bfr[4];
; #pragma unroll
;         for (int m = 0; m < 4; ++m) af[m] = *(const bf16x8*)(sQ + (m * 16 + l15) * 264 + kt * 64 + ks * 32 + lq * 8);
; #pragma unroll
;         for (int n = 0; n < 4; ++n) bfr[n] = *(const bf16x8*)(sT + (w * 64 + n * 16 + l15) * 72 + ks * 32 + lq * 8);
; #pragma unroll
;         for (int m = 0; m < 4; ++m)
; #pragma unroll
;           for (int n = 0; n < 4; ++n) acc[m][n] = MFMA(af[m], bfr[n], acc[m][n]);
;       }
;     }
; #pragma unroll
;     for (int m = 0; m < 4; ++m)
; #pragma unroll
;       for (int j = 0; j < 4; ++j) {
;         float mx = fmaxf(fmaxf(acc[m][0][j], acc[m][1][j]), fmaxf(acc[m][2][j], acc[m][3][j]));
;         mx = row16_max(mx);
;         if (l15 == 0) sMax[w * 64 + m * 16 + lq * 4 + j] = mx;
;       }
	v_mfma_f32_16x16x32_bf16 v[60:63], v[140:143], v[74:77], v[60:63]
	v_mfma_f32_16x16x32_bf16 v[56:59], v[140:143], v[82:85], v[56:59]
	v_mfma_f32_16x16x32_bf16 v[52:55], v[140:143], v[90:93], v[52:55]
	v_mfma_f32_16x16x32_bf16 v[48:51], v[140:143], v[172:175], v[48:51]
	v_mfma_f32_16x16x32_bf16 v[44:47], v[144:147], v[74:77], v[44:47]
	v_mfma_f32_16x16x32_bf16 v[40:43], v[144:147], v[82:85], v[40:43]
	v_mfma_f32_16x16x32_bf16 v[36:39], v[144:147], v[90:93], v[36:39]
	v_mfma_f32_16x16x32_bf16 v[32:35], v[144:147], v[172:175], v[32:35]
	v_mfma_f32_16x16x32_bf16 v[28:31], v[148:151], v[74:77], v[28:31]
	v_mfma_f32_16x16x32_bf16 v[24:27], v[148:151], v[82:85], v[24:27]
	v_mfma_f32_16x16x32_bf16 v[20:23], v[148:151], v[90:93], v[20:23]
	v_mfma_f32_16x16x32_bf16 v[244:247], v[148:151], v[172:175], v[244:247]
	v_mfma_f32_16x16x32_bf16 v[12:15], v[152:155], v[74:77], v[12:15]
	v_mfma_f32_16x16x32_bf16 v[8:11], v[152:155], v[82:85], v[8:11]
	v_mfma_f32_16x16x32_bf16 v[4:7], v[152:155], v[90:93], v[4:7]
	v_mfma_f32_16x16x32_bf16 v[248:251], v[152:155], v[172:175], v[248:251]
	s_waitcnt lgkmcnt(0)
	v_mfma_f32_16x16x32_bf16 v[60:63], v[156:159], v[78:81], v[60:63]
	v_mfma_f32_16x16x32_bf16 v[56:59], v[156:159], v[86:89], v[56:59]
	v_mfma_f32_16x16x32_bf16 v[52:55], v[156:159], v[94:97], v[52:55]
	v_mfma_f32_16x16x32_bf16 v[48:51], v[156:159], v[176:179], v[48:51]
	v_mfma_f32_16x16x32_bf16 v[44:47], v[160:163], v[78:81], v[44:47]
	v_mfma_f32_16x16x32_bf16 v[40:43], v[160:163], v[86:89], v[40:43]
	v_mfma_f32_16x16x32_bf16 v[36:39], v[160:163], v[94:97], v[36:39]
	v_mfma_f32_16x16x32_bf16 v[32:35], v[160:163], v[176:179], v[32:35]
	v_mfma_f32_16x16x32_bf16 v[28:31], v[164:167], v[78:81], v[28:31]
	v_mfma_f32_16x16x32_bf16 v[24:27], v[164:167], v[86:89], v[24:27]
	v_mfma_f32_16x16x32_bf16 v[20:23], v[164:167], v[94:97], v[20:23]
	v_mfma_f32_16x16x32_bf16 v[244:247], v[164:167], v[176:179], v[244:247]
	v_mfma_f32_16x16x32_bf16 v[12:15], v[168:171], v[78:81], v[12:15]
	v_mfma_f32_16x16x32_bf16 v[8:11], v[168:171], v[86:89], v[8:11]
	v_mfma_f32_16x16x32_bf16 v[4:7], v[168:171], v[94:97], v[4:7]
	v_mfma_f32_16x16x32_bf16 v[248:251], v[168:171], v[176:179], v[248:251]
	s_nop 7
	v_max_f32_e32 v2, v52, v52
	v_max_f32_e32 v1, v48, v48
	v_max_f32_e32 v1, v2, v1
	v_max3_f32 v1, v60, v56, v1
	v_and_b32_e32 v96, 0xffffffc0, v16
	v_lshl_add_u32 v0, v96, 2, v125
	s_nop 1
	v_mov_b32_dpp v2, v1 quad_perm:[1,0,3,2] row_mask:0xf bank_mask:0xf bound_ctrl:1
	v_max_f32_e32 v2, v2, v2
	v_max_f32_e32 v1, v1, v2
	s_nop 1
	v_mov_b32_dpp v2, v1 quad_perm:[2,3,0,1] row_mask:0xf bank_mask:0xf bound_ctrl:1
	v_max_f32_e32 v2, v2, v2
	v_max_f32_e32 v1, v1, v2
	s_nop 1
	v_mov_b32_dpp v2, v1 row_half_mirror row_mask:0xf bank_mask:0xf bound_ctrl:1
	v_max_f32_e32 v2, v2, v2
	v_max_f32_e32 v75, v1, v2
	v_add_u32_e32 v74, v0, v64
	s_nop 1
	v_mov_b32_dpp v76, v75 row_ror:8 row_mask:0xf bank_mask:0xf bound_ctrl:1
	s_nop 1
	v_mov_b32_e32 v16, v244
	v_mov_b32_e32 v17, v245
	v_mov_b32_e32 v18, v246
	v_mov_b32_e32 v19, v247
	v_mov_b32_e32 v0, v248
	v_mov_b32_e32 v1, v249
	v_mov_b32_e32 v2, v250
	v_mov_b32_e32 v3, v251
	s_and_saveexec_b64 s[4:5], vcc
	v_max_f32_e32 v76, v76, v76
	v_max_f32_e32 v75, v75, v75
	v_max_f32_e32 v75, v75, v76
	ds_write_b32 v74, v75
	s_or_b64 exec, exec, s[4:5]
	v_max_f32_e32 v75, v49, v49
	v_max_f32_e32 v76, v53, v53
	v_max_f32_e32 v75, v76, v75
	v_max3_f32 v75, v61, v57, v75
	s_nop 1
	v_mov_b32_dpp v76, v75 quad_perm:[1,0,3,2] row_mask:0xf bank_mask:0xf bound_ctrl:1
	v_max_f32_e32 v76, v76, v76
	v_max_f32_e32 v75, v75, v76
	s_nop 1
	v_mov_b32_dpp v76, v75 quad_perm:[2,3,0,1] row_mask:0xf bank_mask:0xf bound_ctrl:1
	v_max_f32_e32 v76, v76, v76
	v_max_f32_e32 v75, v75, v76
	s_nop 1
	v_mov_b32_dpp v76, v75 row_half_mirror row_mask:0xf bank_mask:0xf bound_ctrl:1
	v_max_f32_e32 v76, v76, v76
	v_max_f32_e32 v75, v75, v76
	s_nop 1
	v_mov_b32_dpp v76, v75 row_ror:8 row_mask:0xf bank_mask:0xf bound_ctrl:1
	s_and_saveexec_b64 s[4:5], vcc
	v_max_f32_e32 v76, v76, v76
	v_max_f32_e32 v75, v75, v75
	v_max_f32_e32 v75, v75, v76
	ds_write_b32 v74, v75 offset:4
	s_or_b64 exec, exec, s[4:5]
	v_max_f32_e32 v75, v50, v50
	v_max_f32_e32 v76, v54, v54
	v_max_f32_e32 v75, v76, v75
	v_max3_f32 v75, v62, v58, v75
	s_nop 1
	v_mov_b32_dpp v76, v75 quad_perm:[1,0,3,2] row_mask:0xf bank_mask:0xf bound_ctrl:1
	v_max_f32_e32 v76, v76, v76
	v_max_f32_e32 v75, v75, v76
	s_nop 1
	v_mov_b32_dpp v76, v75 quad_perm:[2,3,0,1] row_mask:0xf bank_mask:0xf bound_ctrl:1
	v_max_f32_e32 v76, v76, v76
	v_max_f32_e32 v75, v75, v76
	s_nop 1
	v_mov_b32_dpp v76, v75 row_half_mirror row_mask:0xf bank_mask:0xf bound_ctrl:1
	v_max_f32_e32 v76, v76, v76
	v_max_f32_e32 v75, v75, v76
	s_nop 1
	v_mov_b32_dpp v76, v75 row_ror:8 row_mask:0xf bank_mask:0xf bound_ctrl:1
	s_and_saveexec_b64 s[4:5], vcc
	v_max_f32_e32 v76, v76, v76
	v_max_f32_e32 v75, v75, v75
	v_max_f32_e32 v75, v75, v76
	ds_write_b32 v74, v75 offset:8
	s_or_b64 exec, exec, s[4:5]
	v_max_f32_e32 v75, v51, v51
	v_max_f32_e32 v76, v55, v55
	v_max_f32_e32 v75, v76, v75
	v_max3_f32 v75, v63, v59, v75
	s_nop 1
	v_mov_b32_dpp v76, v75 quad_perm:[1,0,3,2] row_mask:0xf bank_mask:0xf bound_ctrl:1
	v_max_f32_e32 v76, v76, v76
	v_max_f32_e32 v75, v75, v76
	s_nop 1
	v_mov_b32_dpp v76, v75 quad_perm:[2,3,0,1] row_mask:0xf bank_mask:0xf bound_ctrl:1
	v_max_f32_e32 v76, v76, v76
	v_max_f32_e32 v75, v75, v76
	s_nop 1
	v_mov_b32_dpp v76, v75 row_half_mirror row_mask:0xf bank_mask:0xf bound_ctrl:1
	v_max_f32_e32 v76, v76, v76
	v_max_f32_e32 v75, v75, v76
	s_nop 1
	v_mov_b32_dpp v76, v75 row_ror:8 row_mask:0xf bank_mask:0xf bound_ctrl:1
	s_and_saveexec_b64 s[4:5], vcc
; __device__ __forceinline__ void xattn_item(const Params& p, char* smem, const int tile, const int hm) {
;     ...
; #pragma unroll
;     for (int m = 0; m < 4; ++m)
; #pragma unroll
;       for (int j = 0; j < 4; ++j) {
;         float mx = fmaxf(fmaxf(acc[m][0][j], acc[m][1][j]), fmaxf(acc[m][2][j], acc[m][3][j]));
;         mx = row16_max(mx);
;         if (l15 == 0) sMax[w * 64 + m * 16 + lq * 4 + j] = mx;
;       }
	v_max_f32_e32 v76, v76, v76
	v_max_f32_e32 v75, v75, v75
	v_max_f32_e32 v75, v75, v76
	ds_write_b32 v74, v75 offset:12
	s_or_b64 exec, exec, s[4:5]
	v_max_f32_e32 v75, v32, v32
	v_max_f32_e32 v76, v36, v36
	v_max_f32_e32 v75, v76, v75
	v_max3_f32 v75, v44, v40, v75
	s_nop 1
	v_mov_b32_dpp v76, v75 quad_perm:[1,0,3,2] row_mask:0xf bank_mask:0xf bound_ctrl:1
	v_max_f32_e32 v76, v76, v76
	v_max_f32_e32 v75, v75, v76
	s_nop 1
	v_mov_b32_dpp v76, v75 quad_perm:[2,3,0,1] row_mask:0xf bank_mask:0xf bound_ctrl:1
	v_max_f32_e32 v76, v76, v76
	v_max_f32_e32 v75, v75, v76
	s_nop 1
	v_mov_b32_dpp v76, v75 row_half_mirror row_mask:0xf bank_mask:0xf bound_ctrl:1
	v_max_f32_e32 v76, v76, v76
	v_max_f32_e32 v75, v75, v76
	s_nop 1
	v_mov_b32_dpp v76, v75 row_ror:8 row_mask:0xf bank_mask:0xf bound_ctrl:1
	s_and_saveexec_b64 s[4:5], vcc
	v_max_f32_e32 v76, v76, v76
	v_max_f32_e32 v75, v75, v75
	v_max_f32_e32 v75, v75, v76
	ds_write_b32 v74, v75 offset:64
	s_or_b64 exec, exec, s[4:5]
	v_max_f32_e32 v75, v33, v33
	v_max_f32_e32 v76, v37, v37
	v_max_f32_e32 v75, v76, v75
	v_max3_f32 v75, v45, v41, v75
	s_nop 1
	v_mov_b32_dpp v76, v75 quad_perm:[1,0,3,2] row_mask:0xf bank_mask:0xf bound_ctrl:1
	v_max_f32_e32 v76, v76, v76
	v_max_f32_e32 v75, v75, v76
	s_nop 1
	v_mov_b32_dpp v76, v75 quad_perm:[2,3,0,1] row_mask:0xf bank_mask:0xf bound_ctrl:1
	v_max_f32_e32 v76, v76, v76
	v_max_f32_e32 v75, v75, v76
	s_nop 1
	v_mov_b32_dpp v76, v75 row_half_mirror row_mask:0xf bank_mask:0xf bound_ctrl:1
	v_max_f32_e32 v76, v76, v76
	v_max_f32_e32 v75, v75, v76
	s_nop 1
	v_mov_b32_dpp v76, v75 row_ror:8 row_mask:0xf bank_mask:0xf bound_ctrl:1
	s_and_saveexec_b64 s[4:5], vcc
	v_max_f32_e32 v76, v76, v76
	v_max_f32_e32 v75, v75, v75
	v_max_f32_e32 v75, v75, v76
	ds_write_b32 v74, v75 offset:68
	s_or_b64 exec, exec, s[4:5]
	v_max_f32_e32 v75, v34, v34
	v_max_f32_e32 v76, v38, v38
	v_max_f32_e32 v75, v76, v75
	v_max3_f32 v75, v46, v42, v75
	s_nop 1
	v_mov_b32_dpp v76, v75 quad_perm:[1,0,3,2] row_mask:0xf bank_mask:0xf bound_ctrl:1
	v_max_f32_e32 v76, v76, v76
	v_max_f32_e32 v75, v75, v76
	s_nop 1
	v_mov_b32_dpp v76, v75 quad_perm:[2,3,0,1] row_mask:0xf bank_mask:0xf bound_ctrl:1
	v_max_f32_e32 v76, v76, v76
	v_max_f32_e32 v75, v75, v76
	s_nop 1
	v_mov_b32_dpp v76, v75 row_half_mirror row_mask:0xf bank_mask:0xf bound_ctrl:1
	v_max_f32_e32 v76, v76, v76
	v_max_f32_e32 v75, v75, v76
	s_nop 1
	v_mov_b32_dpp v76, v75 row_ror:8 row_mask:0xf bank_mask:0xf bound_ctrl:1
	s_and_saveexec_b64 s[4:5], vcc
	v_max_f32_e32 v76, v76, v76
	v_max_f32_e32 v75, v75, v75
	v_max_f32_e32 v75, v75, v76
	ds_write_b32 v74, v75 offset:72
	s_or_b64 exec, exec, s[4:5]
	v_max_f32_e32 v75, v35, v35
	v_max_f32_e32 v76, v39, v39
	v_max_f32_e32 v75, v76, v75
	v_max3_f32 v75, v47, v43, v75
	s_nop 1
	v_mov_b32_dpp v76, v75 quad_perm:[1,0,3,2] row_mask:0xf bank_mask:0xf bound_ctrl:1
	v_max_f32_e32 v76, v76, v76
	v_max_f32_e32 v75, v75, v76
	s_nop 1
	v_mov_b32_dpp v76, v75 quad_perm:[2,3,0,1] row_mask:0xf bank_mask:0xf bound_ctrl:1
	v_max_f32_e32 v76, v76, v76
	v_max_f32_e32 v75, v75, v76
	s_nop 1
	v_mov_b32_dpp v76, v75 row_half_mirror row_mask:0xf bank_mask:0xf bound_ctrl:1
	v_max_f32_e32 v76, v76, v76
	v_max_f32_e32 v75, v75, v76
	s_nop 1
	v_mov_b32_dpp v76, v75 row_ror:8 row_mask:0xf bank_mask:0xf bound_ctrl:1
	s_and_saveexec_b64 s[4:5], vcc
	v_max_f32_e32 v76, v76, v76
	v_max_f32_e32 v75, v75, v75
	v_max_f32_e32 v75, v75, v76
	ds_write_b32 v74, v75 offset:76
	s_or_b64 exec, exec, s[4:5]
	v_max_f32_e32 v75, v16, v16
	v_max_f32_e32 v76, v20, v20
	v_max_f32_e32 v75, v76, v75
	v_max3_f32 v75, v28, v24, v75
	s_nop 1
	v_mov_b32_dpp v76, v75 quad_perm:[1,0,3,2] row_mask:0xf bank_mask:0xf bound_ctrl:1
	v_max_f32_e32 v76, v76, v76
	v_max_f32_e32 v75, v75, v76
	s_nop 1
	v_mov_b32_dpp v76, v75 quad_perm:[2,3,0,1] row_mask:0xf bank_mask:0xf bound_ctrl:1
	v_max_f32_e32 v76, v76, v76
	v_max_f32_e32 v75, v75, v76
	s_nop 1
	v_mov_b32_dpp v76, v75 row_half_mirror row_mask:0xf bank_mask:0xf bound_ctrl:1
	v_max_f32_e32 v76, v76, v76
	v_max_f32_e32 v75, v75, v76
	s_nop 1
	v_mov_b32_dpp v76, v75 row_ror:8 row_mask:0xf bank_mask:0xf bound_ctrl:1
	s_and_saveexec_b64 s[4:5], vcc
	v_max_f32_e32 v76, v76, v76
	v_max_f32_e32 v75, v75, v75
	v_max_f32_e32 v75, v75, v76
	ds_write_b32 v74, v75 offset:128
	s_or_b64 exec, exec, s[4:5]
	v_max_f32_e32 v75, v17, v17
	v_max_f32_e32 v76, v21, v21
	v_max_f32_e32 v75, v76, v75
	v_max3_f32 v75, v29, v25, v75
	s_nop 1
	v_mov_b32_dpp v76, v75 quad_perm:[1,0,3,2] row_mask:0xf bank_mask:0xf bound_ctrl:1
	v_max_f32_e32 v76, v76, v76
	v_max_f32_e32 v75, v75, v76
	s_nop 1
	v_mov_b32_dpp v76, v75 quad_perm:[2,3,0,1] row_mask:0xf bank_mask:0xf bound_ctrl:1
	v_max_f32_e32 v76, v76, v76
	v_max_f32_e32 v75, v75, v76
	s_nop 1
	v_mov_b32_dpp v76, v75 row_half_mirror row_mask:0xf bank_mask:0xf bound_ctrl:1
	v_max_f32_e32 v76, v76, v76
	v_max_f32_e32 v75, v75, v76
	s_nop 1
	v_mov_b32_dpp v76, v75 row_ror:8 row_mask:0xf bank_mask:0xf bound_ctrl:1
	s_and_saveexec_b64 s[4:5], vcc
	v_max_f32_e32 v76, v76, v76
	v_max_f32_e32 v75, v75, v75
	v_max_f32_e32 v75, v75, v76
	ds_write_b32 v74, v75 offset:132
	s_or_b64 exec, exec, s[4:5]
	v_max_f32_e32 v75, v18, v18
	v_max_f32_e32 v76, v22, v22
	v_max_f32_e32 v75, v76, v75
	v_max3_f32 v75, v30, v26, v75
	s_nop 1
	v_mov_b32_dpp v76, v75 quad_perm:[1,0,3,2] row_mask:0xf bank_mask:0xf bound_ctrl:1
	v_max_f32_e32 v76, v76, v76
	v_max_f32_e32 v75, v75, v76
	s_nop 1
	v_mov_b32_dpp v76, v75 quad_perm:[2,3,0,1] row_mask:0xf bank_mask:0xf bound_ctrl:1
	v_max_f32_e32 v76, v76, v76
	v_max_f32_e32 v75, v75, v76
	s_nop 1
	v_mov_b32_dpp v76, v75 row_half_mirror row_mask:0xf bank_mask:0xf bound_ctrl:1
; __device__ __forceinline__ void xattn_item(const Params& p, char* smem, const int tile, const int hm) {
;     ...
; #pragma unroll
;     for (int m = 0; m < 4; ++m)
; #pragma unroll
;       for (int j = 0; j < 4; ++j) {
;         float mx = fmaxf(fmaxf(acc[m][0][j], acc[m][1][j]), fmaxf(acc[m][2][j], acc[m][3][j]));
;         mx = row16_max(mx);
;         if (l15 == 0) sMax[w * 64 + m * 16 + lq * 4 + j] = mx;
;       }
;     __syncthreads();
	v_max_f32_e32 v76, v76, v76
	v_max_f32_e32 v75, v75, v76
	s_nop 1
	v_mov_b32_dpp v76, v75 row_ror:8 row_mask:0xf bank_mask:0xf bound_ctrl:1
	s_and_saveexec_b64 s[4:5], vcc
	v_max_f32_e32 v76, v76, v76
	v_max_f32_e32 v75, v75, v75
	v_max_f32_e32 v75, v75, v76
	ds_write_b32 v74, v75 offset:136
	s_or_b64 exec, exec, s[4:5]
	v_max_f32_e32 v75, v19, v19
	v_max_f32_e32 v76, v23, v23
	v_max_f32_e32 v75, v76, v75
	v_max3_f32 v75, v31, v27, v75
	s_nop 1
	v_mov_b32_dpp v76, v75 quad_perm:[1,0,3,2] row_mask:0xf bank_mask:0xf bound_ctrl:1
	v_max_f32_e32 v76, v76, v76
	v_max_f32_e32 v75, v75, v76
	s_nop 1
	v_mov_b32_dpp v76, v75 quad_perm:[2,3,0,1] row_mask:0xf bank_mask:0xf bound_ctrl:1
	v_max_f32_e32 v76, v76, v76
	v_max_f32_e32 v75, v75, v76
	s_nop 1
	v_mov_b32_dpp v76, v75 row_half_mirror row_mask:0xf bank_mask:0xf bound_ctrl:1
	v_max_f32_e32 v76, v76, v76
	v_max_f32_e32 v75, v75, v76
	s_nop 1
	v_mov_b32_dpp v76, v75 row_ror:8 row_mask:0xf bank_mask:0xf bound_ctrl:1
	s_and_saveexec_b64 s[4:5], vcc
	v_max_f32_e32 v76, v76, v76
	v_max_f32_e32 v75, v75, v75
	v_max_f32_e32 v75, v75, v76
	ds_write_b32 v74, v75 offset:140
	s_or_b64 exec, exec, s[4:5]
	v_max_f32_e32 v75, v0, v0
	v_max_f32_e32 v76, v4, v4
	v_max_f32_e32 v75, v76, v75
	v_max3_f32 v75, v12, v8, v75
	s_nop 1
	v_mov_b32_dpp v76, v75 quad_perm:[1,0,3,2] row_mask:0xf bank_mask:0xf bound_ctrl:1
	v_max_f32_e32 v76, v76, v76
	v_max_f32_e32 v75, v75, v76
	s_nop 1
	v_mov_b32_dpp v76, v75 quad_perm:[2,3,0,1] row_mask:0xf bank_mask:0xf bound_ctrl:1
	v_max_f32_e32 v76, v76, v76
	v_max_f32_e32 v75, v75, v76
	s_nop 1
	v_mov_b32_dpp v76, v75 row_half_mirror row_mask:0xf bank_mask:0xf bound_ctrl:1
	v_max_f32_e32 v76, v76, v76
	v_max_f32_e32 v75, v75, v76
	s_nop 1
	v_mov_b32_dpp v76, v75 row_ror:8 row_mask:0xf bank_mask:0xf bound_ctrl:1
	s_and_saveexec_b64 s[4:5], vcc
	v_max_f32_e32 v76, v76, v76
	v_max_f32_e32 v75, v75, v75
	v_max_f32_e32 v75, v75, v76
	ds_write_b32 v74, v75 offset:192
	s_or_b64 exec, exec, s[4:5]
	v_max_f32_e32 v75, v1, v1
	v_max_f32_e32 v76, v5, v5
	v_max_f32_e32 v75, v76, v75
	v_max3_f32 v75, v13, v9, v75
	s_nop 1
	v_mov_b32_dpp v76, v75 quad_perm:[1,0,3,2] row_mask:0xf bank_mask:0xf bound_ctrl:1
	v_max_f32_e32 v76, v76, v76
	v_max_f32_e32 v75, v75, v76
	s_nop 1
	v_mov_b32_dpp v76, v75 quad_perm:[2,3,0,1] row_mask:0xf bank_mask:0xf bound_ctrl:1
	v_max_f32_e32 v76, v76, v76
	v_max_f32_e32 v75, v75, v76
	s_nop 1
	v_mov_b32_dpp v76, v75 row_half_mirror row_mask:0xf bank_mask:0xf bound_ctrl:1
	v_max_f32_e32 v76, v76, v76
	v_max_f32_e32 v75, v75, v76
	s_nop 1
	v_mov_b32_dpp v76, v75 row_ror:8 row_mask:0xf bank_mask:0xf bound_ctrl:1
	s_and_saveexec_b64 s[4:5], vcc
	v_max_f32_e32 v76, v76, v76
	v_max_f32_e32 v75, v75, v75
	v_max_f32_e32 v75, v75, v76
	ds_write_b32 v74, v75 offset:196
	s_or_b64 exec, exec, s[4:5]
	v_max_f32_e32 v75, v2, v2
	v_max_f32_e32 v76, v6, v6
	v_max_f32_e32 v75, v76, v75
	v_max3_f32 v75, v14, v10, v75
	s_nop 1
	v_mov_b32_dpp v76, v75 quad_perm:[1,0,3,2] row_mask:0xf bank_mask:0xf bound_ctrl:1
	v_max_f32_e32 v76, v76, v76
	v_max_f32_e32 v75, v75, v76
	s_nop 1
	v_mov_b32_dpp v76, v75 quad_perm:[2,3,0,1] row_mask:0xf bank_mask:0xf bound_ctrl:1
	v_max_f32_e32 v76, v76, v76
	v_max_f32_e32 v75, v75, v76
	s_nop 1
	v_mov_b32_dpp v76, v75 row_half_mirror row_mask:0xf bank_mask:0xf bound_ctrl:1
	v_max_f32_e32 v76, v76, v76
	v_max_f32_e32 v75, v75, v76
	s_nop 1
	v_mov_b32_dpp v76, v75 row_ror:8 row_mask:0xf bank_mask:0xf bound_ctrl:1
	s_and_saveexec_b64 s[4:5], vcc
	v_max_f32_e32 v76, v76, v76
	v_max_f32_e32 v75, v75, v75
	v_max_f32_e32 v75, v75, v76
	ds_write_b32 v74, v75 offset:200
	s_or_b64 exec, exec, s[4:5]
	v_max_f32_e32 v75, v3, v3
	v_max_f32_e32 v76, v7, v7
	v_max_f32_e32 v75, v76, v75
	v_max3_f32 v75, v15, v11, v75
	s_nop 1
	v_mov_b32_dpp v76, v75 quad_perm:[1,0,3,2] row_mask:0xf bank_mask:0xf bound_ctrl:1
	v_max_f32_e32 v76, v76, v76
	v_max_f32_e32 v75, v75, v76
	s_nop 1
	v_mov_b32_dpp v76, v75 quad_perm:[2,3,0,1] row_mask:0xf bank_mask:0xf bound_ctrl:1
	v_max_f32_e32 v76, v76, v76
	v_max_f32_e32 v75, v75, v76
	s_nop 1
	v_mov_b32_dpp v76, v75 row_half_mirror row_mask:0xf bank_mask:0xf bound_ctrl:1
	v_max_f32_e32 v76, v76, v76
	v_max_f32_e32 v75, v75, v76
	s_nop 1
	v_mov_b32_dpp v76, v75 row_ror:8 row_mask:0xf bank_mask:0xf bound_ctrl:1
	s_and_saveexec_b64 s[4:5], vcc
	v_max_f32_e32 v76, v76, v76
	v_max_f32_e32 v75, v75, v75
	v_max_f32_e32 v75, v75, v76
	ds_write_b32 v74, v75 offset:204
	s_or_b64 exec, exec, s[4:5]
	v_or_b32_e32 v74, 0x11400, v64
	v_or_b32_e32 v75, 0x11500, v64
	v_or_b32_e32 v76, 0x11600, v64
	v_or_b32_e32 v77, 0x11700, v64
	s_waitcnt lgkmcnt(0)
	s_barrier
; __device__ __forceinline__ void xattn_item(const Params& p, char* smem, const int tile, const int hm) {
;     ...
; #pragma unroll
;     for (int m = 0; m < 4; ++m)
; #pragma unroll
;       for (int j = 0; j < 4; ++j) {
;         const int row = m * 16 + lq * 4 + j;
;         const float gmx = fmaxf(fmaxf(sMax[row], sMax[64 + row]), fmaxf(sMax[128 + row], sMax[192 + row]));
;         float sum = 0.f;
; #pragma unroll
;         for (int n = 0; n < 4; ++n) {
;           const float e = __expf((acc[m][n][j] - gmx) * 0.0625f);
;           sum += e;
;           sQ[row * 264 + w * 64 + n * 16 + l15] = f2bf(e);
;         }
;         sum = row16_sum(sum);
;         if (l15 == 0) sSum[w * 64 + row] = sum;
;       }
	ds_read_b32 v76, v76
	ds_read_b32 v77, v77
	ds_read_b32 v74, v74
	ds_read_b32 v75, v75
	v_lshlrev_b32_e32 v78, 1, v112
	s_waitcnt lgkmcnt(3)
	v_max_f32_e32 v76, v76, v76
	s_waitcnt lgkmcnt(2)
	v_max_f32_e32 v77, v77, v77
	v_max_f32_e32 v76, v76, v77
	s_waitcnt lgkmcnt(0)
	v_max3_f32 v74, v74, v75, v76
	v_sub_f32_e32 v60, v60, v74
	v_mul_f32_e32 v60, 0x3d800000, v60
	v_mul_f32_e32 v60, 0x3fb8aa3b, v60
	v_sub_f32_e32 v56, v56, v74
	v_exp_f32_e32 v75, v60
	v_mul_f32_e32 v56, 0x3d800000, v56
	v_sub_f32_e32 v52, v52, v74
	v_mul_f32_e32 v56, 0x3fb8aa3b, v56
	v_mul_f32_e32 v52, 0x3d800000, v52
	v_exp_f32_e32 v56, v56
	v_mul_f32_e32 v52, 0x3fb8aa3b, v52
	v_sub_f32_e32 v48, v48, v74
	v_exp_f32_e32 v52, v52
	v_mul_f32_e32 v48, 0x3d800000, v48
	v_lshl_add_u32 v60, v96, 1, v78
	v_bfe_u32 v78, v75, 16, 1
	v_mul_f32_e32 v48, 0x3fb8aa3b, v48
	v_lshlrev_b32_e32 v113, 2, v73
	v_mad_u32_u24 v73, v73, s83, v60
	v_add_f32_e32 v77, 0, v75
	v_add3_u32 v75, v75, v78, s77
	v_exp_f32_e32 v48, v48
	ds_write_b16_d16_hi v73, v75
	v_add_f32_e32 v75, v56, v77
	v_bfe_u32 v77, v56, 16, 1
	v_add3_u32 v56, v56, v77, s77
	v_bfe_u32 v74, v52, 16, 1
	ds_write_b16_d16_hi v73, v56 offset:32
	v_add_f32_e32 v56, v52, v75
	v_add3_u32 v52, v52, v74, s77
	ds_write_b16_d16_hi v73, v52 offset:64
	v_add_f32_e32 v52, v48, v56
	v_bfe_u32 v56, v48, 16, 1
	v_add3_u32 v48, v48, v56, s77
	ds_write_b16_d16_hi v73, v48 offset:96
	v_lshl_add_u32 v76, v96, 2, v194
	v_add_f32_dpp v48, v52, v52 quad_perm:[1,0,3,2] row_mask:0xf bank_mask:0xf bound_ctrl:1
	s_nop 1
	v_add_f32_dpp v48, v48, v48 quad_perm:[2,3,0,1] row_mask:0xf bank_mask:0xf bound_ctrl:1
	s_nop 1
	v_add_f32_dpp v52, v48, v48 row_half_mirror row_mask:0xf bank_mask:0xf bound_ctrl:1
	v_lshl_add_u32 v48, v113, 2, v76
	s_nop 0
	v_mov_b32_dpp v56, v52 row_ror:8 row_mask:0xf bank_mask:0xf bound_ctrl:1
	s_and_saveexec_b64 s[4:5], vcc
	v_add_f32_e32 v52, v52, v56
	ds_write_b32 v48, v52
	s_or_b64 exec, exec, s[4:5]
	v_or_b32_e32 v52, 1, v113
	v_lshlrev_b32_e32 v56, 2, v52
	v_or_b32_e32 v73, 0x11400, v56
	v_or_b32_e32 v74, 0x11500, v56
	v_or_b32_e32 v75, 0x11600, v56
	v_or_b32_e32 v56, 0x11700, v56
	ds_read_b32 v56, v56
	ds_read_b32 v75, v75
	ds_read_b32 v73, v73
	ds_read_b32 v74, v74
	s_waitcnt lgkmcnt(3)
	v_max_f32_e32 v56, v56, v56
	s_waitcnt lgkmcnt(2)
	v_max_f32_e32 v75, v75, v75
	v_max_f32_e32 v56, v75, v56
	s_waitcnt lgkmcnt(0)
	v_max3_f32 v56, v73, v74, v56
	v_sub_f32_e32 v61, v61, v56
	v_mul_f32_e32 v61, 0x3d800000, v61
	v_mul_f32_e32 v61, 0x3fb8aa3b, v61
	v_sub_f32_e32 v57, v57, v56
	v_exp_f32_e32 v61, v61
	v_mul_f32_e32 v57, 0x3d800000, v57
	v_sub_f32_e32 v53, v53, v56
	v_mul_f32_e32 v57, 0x3fb8aa3b, v57
	v_mul_f32_e32 v53, 0x3d800000, v53
	v_sub_f32_e32 v49, v49, v56
	v_exp_f32_e32 v57, v57
	v_mul_f32_e32 v53, 0x3fb8aa3b, v53
	v_mul_f32_e32 v49, 0x3d800000, v49
	v_exp_f32_e32 v53, v53
	v_mul_f32_e32 v49, 0x3fb8aa3b, v49
	v_bfe_u32 v75, v61, 16, 1
	v_exp_f32_e32 v49, v49
	v_mad_u32_u24 v73, v52, s81, v60
	v_add_f32_e32 v74, 0, v61
	v_add3_u32 v61, v61, v75, s77
	ds_write_b16_d16_hi v73, v61
	v_add_f32_e32 v61, v57, v74
	v_bfe_u32 v74, v57, 16, 1
	v_add3_u32 v57, v57, v74, s77
	v_bfe_u32 v56, v53, 16, 1
	ds_write_b16_d16_hi v73, v57 offset:32
	v_add_f32_e32 v57, v53, v61
	v_add3_u32 v53, v53, v56, s77
	v_bfe_u32 v56, v49, 16, 1
	ds_write_b16_d16_hi v73, v53 offset:64
	v_add_f32_e32 v53, v49, v57
	v_add3_u32 v49, v49, v56, s77
	ds_write_b16_d16_hi v73, v49 offset:96
	s_nop 0
	v_add_f32_dpp v49, v53, v53 quad_perm:[1,0,3,2] row_mask:0xf bank_mask:0xf bound_ctrl:1
	s_nop 1
	v_add_f32_dpp v49, v49, v49 quad_perm:[2,3,0,1] row_mask:0xf bank_mask:0xf bound_ctrl:1
	s_nop 1
	v_add_f32_dpp v49, v49, v49 row_half_mirror row_mask:0xf bank_mask:0xf bound_ctrl:1
	s_nop 1
	v_mov_b32_dpp v53, v49 row_ror:8 row_mask:0xf bank_mask:0xf bound_ctrl:1
	s_and_saveexec_b64 s[4:5], vcc
	v_add_f32_e32 v49, v49, v53
	ds_write_b32 v48, v49 offset:4
	s_or_b64 exec, exec, s[4:5]
	v_lshl_add_u32 v49, v113, 2, v195
	ds_read2st64_b32 v[56:57], v49 offset0:2 offset1:3
	ds_read2st64_b32 v[74:75], v49 offset1:1
	v_mul_u32_u24_e32 v49, 0x210, v52
	v_add_u32_e32 v49, 0x210, v49
	s_waitcnt lgkmcnt(1)
	v_max_f32_e32 v52, v57, v57
	v_max_f32_e32 v53, v56, v56
	v_max_f32_e32 v52, v53, v52
	s_waitcnt lgkmcnt(0)
	v_max3_f32 v52, v74, v75, v52
	v_sub_f32_e32 v53, v62, v52
	v_mul_f32_e32 v53, 0x3d800000, v53
	v_mul_f32_e32 v53, 0x3fb8aa3b, v53
	v_sub_f32_e32 v57, v58, v52
	v_sub_f32_e32 v54, v54, v52
	v_exp_f32_e32 v53, v53
	v_mul_f32_e32 v57, 0x3d800000, v57
	v_mul_f32_e32 v54, 0x3d800000, v54
	v_mul_f32_e32 v57, 0x3fb8aa3b, v57
	v_mul_f32_e32 v54, 0x3fb8aa3b, v54
	v_sub_f32_e32 v50, v50, v52
	v_exp_f32_e32 v57, v57
	v_exp_f32_e32 v54, v54
	v_mul_f32_e32 v50, 0x3d800000, v50
	v_mul_f32_e32 v50, 0x3fb8aa3b, v50
	v_bfe_u32 v61, v53, 16, 1
	v_exp_f32_e32 v50, v50
	v_add_u32_e32 v56, v60, v49
	v_add_f32_e32 v58, 0, v53
	v_add3_u32 v53, v53, v61, s77
	ds_write_b16_d16_hi v56, v53
	v_add_f32_e32 v53, v57, v58
	v_bfe_u32 v52, v54, 16, 1
	v_add_f32_e32 v53, v54, v53
	v_add3_u32 v52, v54, v52, s77
	ds_write_b16_d16_hi v56, v52 offset:64
	v_add_f32_e32 v52, v50, v53
	v_bfe_u32 v53, v50, 16, 1
	v_add3_u32 v50, v50, v53, s77
	ds_write_b16_d16_hi v56, v50 offset:96
	v_bfe_u32 v58, v57, 16, 1
	v_add_f32_dpp v50, v52, v52 quad_perm:[1,0,3,2] row_mask:0xf bank_mask:0xf bound_ctrl:1
	v_add3_u32 v57, v57, v58, s77
	ds_write_b16_d16_hi v56, v57 offset:32
	v_add_f32_dpp v50, v50, v50 quad_perm:[2,3,0,1] row_mask:0xf bank_mask:0xf bound_ctrl:1
	s_nop 1
	v_add_f32_dpp v50, v50, v50 row_half_mirror row_mask:0xf bank_mask:0xf bound_ctrl:1
	s_nop 1
	v_mov_b32_dpp v52, v50 row_ror:8 row_mask:0xf bank_mask:0xf bound_ctrl:1
	s_and_saveexec_b64 s[4:5], vcc
	v_add_f32_e32 v50, v50, v52
	ds_write_b32 v48, v50 offset:8
	s_or_b64 exec, exec, s[4:5]
	v_lshl_add_u32 v50, v113, 2, v196
	ds_read2st64_b32 v[52:53], v50 offset0:2 offset1:3
	ds_read2st64_b32 v[56:57], v50 offset1:1
	v_add_u32_e32 v50, 0x210, v49
	v_add_u32_e32 v49, v60, v50
	s_waitcnt lgkmcnt(1)
; __device__ __forceinline__ void xattn_item(const Params& p, char* smem, const int tile, const int hm) {
;     ...
; #pragma unroll
;     for (int m = 0; m < 4; ++m)
; #pragma unroll
;       for (int j = 0; j < 4; ++j) {
;         const int row = m * 16 + lq * 4 + j;
;         const float gmx = fmaxf(fmaxf(sMax[row], sMax[64 + row]), fmaxf(sMax[128 + row], sMax[192 + row]));
;         float sum = 0.f;
; #pragma unroll
;         for (int n = 0; n < 4; ++n) {
;           const float e = __expf((acc[m][n][j] - gmx) * 0.0625f);
;           sum += e;
;           sQ[row * 264 + w * 64 + n * 16 + l15] = f2bf(e);
;         }
;         sum = row16_sum(sum);
;         if (l15 == 0) sSum[w * 64 + row] = sum;
;       }
	v_max_f32_e32 v53, v53, v53
	v_max_f32_e32 v52, v52, v52
	v_max_f32_e32 v52, v52, v53
	s_waitcnt lgkmcnt(0)
	v_max3_f32 v52, v56, v57, v52
	v_sub_f32_e32 v53, v63, v52
	v_mul_f32_e32 v53, 0x3d800000, v53
	v_mul_f32_e32 v53, 0x3fb8aa3b, v53
	v_sub_f32_e32 v54, v59, v52
	v_sub_f32_e32 v55, v55, v52
	v_exp_f32_e32 v53, v53
	v_mul_f32_e32 v54, 0x3d800000, v54
	v_mul_f32_e32 v55, 0x3d800000, v55
	v_mul_f32_e32 v54, 0x3fb8aa3b, v54
	v_mul_f32_e32 v55, 0x3fb8aa3b, v55
	v_sub_f32_e32 v51, v51, v52
	v_exp_f32_e32 v54, v54
	v_exp_f32_e32 v55, v55
	v_mul_f32_e32 v51, 0x3d800000, v51
	v_mul_f32_e32 v51, 0x3fb8aa3b, v51
	v_bfe_u32 v57, v53, 16, 1
	v_exp_f32_e32 v51, v51
	v_add_f32_e32 v56, 0, v53
	v_add3_u32 v53, v53, v57, s77
	ds_write_b16_d16_hi v49, v53
	v_add_f32_e32 v53, v54, v56
	v_bfe_u32 v52, v55, 16, 1
	v_add_f32_e32 v53, v55, v53
	v_add3_u32 v52, v55, v52, s77
	v_bfe_u32 v56, v54, 16, 1
	ds_write_b16_d16_hi v49, v52 offset:64
	v_add_f32_e32 v52, v51, v53
	v_bfe_u32 v53, v51, 16, 1
	v_add3_u32 v54, v54, v56, s77
	v_add3_u32 v51, v51, v53, s77
	ds_write_b16_d16_hi v49, v54 offset:32
	ds_write_b16_d16_hi v49, v51 offset:96
	v_add_f32_dpp v49, v52, v52 quad_perm:[1,0,3,2] row_mask:0xf bank_mask:0xf bound_ctrl:1
	s_nop 1
	v_add_f32_dpp v49, v49, v49 quad_perm:[2,3,0,1] row_mask:0xf bank_mask:0xf bound_ctrl:1
	s_nop 1
	v_add_f32_dpp v49, v49, v49 row_half_mirror row_mask:0xf bank_mask:0xf bound_ctrl:1
	s_nop 1
	v_mov_b32_dpp v51, v49 row_ror:8 row_mask:0xf bank_mask:0xf bound_ctrl:1
	s_and_saveexec_b64 s[4:5], vcc
	v_add_f32_e32 v49, v49, v51
	ds_write_b32 v48, v49 offset:12
	s_or_b64 exec, exec, s[4:5]
	v_lshlrev_b32_e32 v49, 2, v113
	v_or_b32_e32 v51, 0x11440, v49
	v_or_b32_e32 v52, 0x11540, v49
	v_or_b32_e32 v53, 0x11640, v49
	v_or_b32_e32 v54, 0x11740, v49
	ds_read_b32 v54, v54
	ds_read_b32 v53, v53
	ds_read_b32 v51, v51
	ds_read_b32 v52, v52
	s_waitcnt lgkmcnt(3)
	v_max_f32_e32 v54, v54, v54
	s_waitcnt lgkmcnt(2)
	v_max_f32_e32 v53, v53, v53
	v_max_f32_e32 v53, v53, v54
	s_waitcnt lgkmcnt(0)
	v_max3_f32 v51, v51, v52, v53
	v_sub_f32_e32 v44, v44, v51
	v_mul_f32_e32 v44, 0x3d800000, v44
	v_mul_f32_e32 v44, 0x3fb8aa3b, v44
	v_sub_f32_e32 v40, v40, v51
	v_exp_f32_e32 v52, v44
	v_mul_f32_e32 v40, 0x3d800000, v40
	v_sub_f32_e32 v36, v36, v51
	v_mul_f32_e32 v40, 0x3fb8aa3b, v40
	v_mul_f32_e32 v36, 0x3d800000, v36
	v_exp_f32_e32 v40, v40
	v_mul_f32_e32 v36, 0x3fb8aa3b, v36
	v_sub_f32_e32 v32, v32, v51
	v_exp_f32_e32 v36, v36
	v_mul_f32_e32 v32, 0x3d800000, v32
	v_add_u32_e32 v44, 0x1ad0, v50
	v_bfe_u32 v54, v52, 16, 1
	v_mul_f32_e32 v32, 0x3fb8aa3b, v32
	v_add_u32_e32 v50, v60, v44
	v_add_f32_e32 v53, 0, v52
	v_add3_u32 v52, v52, v54, s77
	v_exp_f32_e32 v32, v32
	ds_write_b16_d16_hi v50, v52
	v_add_f32_e32 v52, v40, v53
	v_bfe_u32 v53, v40, 16, 1
	v_add3_u32 v40, v40, v53, s77
	v_bfe_u32 v51, v36, 16, 1
	ds_write_b16_d16_hi v50, v40 offset:32
	v_add_f32_e32 v40, v36, v52
	v_add3_u32 v36, v36, v51, s77
	ds_write_b16_d16_hi v50, v36 offset:64
	v_add_f32_e32 v36, v32, v40
	v_bfe_u32 v40, v32, 16, 1
	v_add3_u32 v32, v32, v40, s77
	ds_write_b16_d16_hi v50, v32 offset:96
	s_nop 0
	v_add_f32_dpp v32, v36, v36 quad_perm:[1,0,3,2] row_mask:0xf bank_mask:0xf bound_ctrl:1
	s_nop 1
	v_add_f32_dpp v32, v32, v32 quad_perm:[2,3,0,1] row_mask:0xf bank_mask:0xf bound_ctrl:1
	s_nop 1
	v_add_f32_dpp v32, v32, v32 row_half_mirror row_mask:0xf bank_mask:0xf bound_ctrl:1
	s_nop 1
	v_mov_b32_dpp v36, v32 row_ror:8 row_mask:0xf bank_mask:0xf bound_ctrl:1
	s_and_saveexec_b64 s[4:5], vcc
	v_add_f32_e32 v32, v32, v36
	ds_write_b32 v48, v32 offset:64
	s_or_b64 exec, exec, s[4:5]
	v_lshl_add_u32 v32, v113, 2, v206
	ds_read2st64_b32 v[50:51], v32 offset0:2 offset1:3
	ds_read2st64_b32 v[52:53], v32 offset1:1
	v_add_u32_e32 v32, 0x210, v44
	v_add_u32_e32 v36, v60, v32
	s_waitcnt lgkmcnt(1)
	v_max_f32_e32 v40, v51, v51
	v_max_f32_e32 v44, v50, v50
	v_max_f32_e32 v40, v44, v40
	s_waitcnt lgkmcnt(0)
	v_max3_f32 v40, v52, v53, v40
	v_sub_f32_e32 v44, v45, v40
	v_mul_f32_e32 v44, 0x3d800000, v44
	v_mul_f32_e32 v44, 0x3fb8aa3b, v44
	v_sub_f32_e32 v41, v41, v40
	v_exp_f32_e32 v44, v44
	v_mul_f32_e32 v41, 0x3d800000, v41
	v_sub_f32_e32 v37, v37, v40
	v_mul_f32_e32 v41, 0x3fb8aa3b, v41
	v_mul_f32_e32 v37, 0x3d800000, v37
	v_sub_f32_e32 v33, v33, v40
	v_exp_f32_e32 v41, v41
	v_mul_f32_e32 v37, 0x3fb8aa3b, v37
	v_mul_f32_e32 v33, 0x3d800000, v33
	v_exp_f32_e32 v37, v37
	v_mul_f32_e32 v33, 0x3fb8aa3b, v33
	v_bfe_u32 v50, v44, 16, 1
	v_exp_f32_e32 v33, v33
	v_add_f32_e32 v45, 0, v44
	v_add3_u32 v44, v44, v50, s77
	ds_write_b16_d16_hi v36, v44
	v_add_f32_e32 v44, v41, v45
	v_bfe_u32 v45, v41, 16, 1
	v_add3_u32 v41, v41, v45, s77
	v_bfe_u32 v40, v37, 16, 1
	ds_write_b16_d16_hi v36, v41 offset:32
	v_add_f32_e32 v41, v37, v44
	v_add3_u32 v37, v37, v40, s77
	v_bfe_u32 v40, v33, 16, 1
	ds_write_b16_d16_hi v36, v37 offset:64
	v_add_f32_e32 v37, v33, v41
	v_add3_u32 v33, v33, v40, s77
	ds_write_b16_d16_hi v36, v33 offset:96
	s_nop 0
	v_add_f32_dpp v33, v37, v37 quad_perm:[1,0,3,2] row_mask:0xf bank_mask:0xf bound_ctrl:1
	s_nop 1
	v_add_f32_dpp v33, v33, v33 quad_perm:[2,3,0,1] row_mask:0xf bank_mask:0xf bound_ctrl:1
	s_nop 1
	v_add_f32_dpp v33, v33, v33 row_half_mirror row_mask:0xf bank_mask:0xf bound_ctrl:1
	s_nop 1
	v_mov_b32_dpp v36, v33 row_ror:8 row_mask:0xf bank_mask:0xf bound_ctrl:1
	s_and_saveexec_b64 s[4:5], vcc
	v_add_f32_e32 v33, v33, v36
	ds_write_b32 v48, v33 offset:68
	s_or_b64 exec, exec, s[4:5]
	v_lshl_add_u32 v33, v113, 2, v130
	ds_read2st64_b32 v[36:37], v33 offset0:2 offset1:3
	ds_read2st64_b32 v[40:41], v33 offset1:1
	v_add_u32_e32 v32, 0x210, v32
	v_add_u32_e32 v32, v60, v32
	s_waitcnt lgkmcnt(1)
; __device__ __forceinline__ void xattn_item(const Params& p, char* smem, const int tile, const int hm) {
;     ...
; #pragma unroll
;     for (int m = 0; m < 4; ++m)
; #pragma unroll
;       for (int j = 0; j < 4; ++j) {
;         const int row = m * 16 + lq * 4 + j;
;         const float gmx = fmaxf(fmaxf(sMax[row], sMax[64 + row]), fmaxf(sMax[128 + row], sMax[192 + row]));
;         float sum = 0.f;
; #pragma unroll
;         for (int n = 0; n < 4; ++n) {
;           const float e = __expf((acc[m][n][j] - gmx) * 0.0625f);
;           sum += e;
;           sQ[row * 264 + w * 64 + n * 16 + l15] = f2bf(e);
;         }
;         sum = row16_sum(sum);
;         if (l15 == 0) sSum[w * 64 + row] = sum;
;       }
	v_max_f32_e32 v33, v37, v37
	v_max_f32_e32 v36, v36, v36
	v_max_f32_e32 v33, v36, v33
	s_waitcnt lgkmcnt(0)
	v_max3_f32 v33, v40, v41, v33
	v_sub_f32_e32 v36, v46, v33
	v_mul_f32_e32 v36, 0x3d800000, v36
	v_mul_f32_e32 v36, 0x3fb8aa3b, v36
	v_sub_f32_e32 v37, v42, v33
	v_sub_f32_e32 v38, v38, v33
	v_exp_f32_e32 v36, v36
	v_mul_f32_e32 v37, 0x3d800000, v37
	v_mul_f32_e32 v38, 0x3d800000, v38
	v_mul_f32_e32 v37, 0x3fb8aa3b, v37
	v_mul_f32_e32 v38, 0x3fb8aa3b, v38
	v_sub_f32_e32 v33, v34, v33
	v_exp_f32_e32 v37, v37
	v_exp_f32_e32 v38, v38
	v_mul_f32_e32 v33, 0x3d800000, v33
	v_mul_f32_e32 v33, 0x3fb8aa3b, v33
	v_bfe_u32 v41, v36, 16, 1
	v_exp_f32_e32 v33, v33
	v_add_f32_e32 v40, 0, v36
	v_add3_u32 v36, v36, v41, s77
	ds_write_b16_d16_hi v32, v36
	v_add_f32_e32 v36, v37, v40
	v_bfe_u32 v34, v38, 16, 1
	v_add_f32_e32 v36, v38, v36
	v_add3_u32 v34, v38, v34, s77
	ds_write_b16_d16_hi v32, v34 offset:64
	v_add_f32_e32 v34, v33, v36
	v_bfe_u32 v36, v33, 16, 1
	v_add3_u32 v33, v33, v36, s77
	ds_write_b16_d16_hi v32, v33 offset:96
	v_bfe_u32 v40, v37, 16, 1
	v_add_f32_dpp v33, v34, v34 quad_perm:[1,0,3,2] row_mask:0xf bank_mask:0xf bound_ctrl:1
	v_add3_u32 v37, v37, v40, s77
	ds_write_b16_d16_hi v32, v37 offset:32
	v_add_f32_dpp v33, v33, v33 quad_perm:[2,3,0,1] row_mask:0xf bank_mask:0xf bound_ctrl:1
	s_nop 1
	v_add_f32_dpp v33, v33, v33 row_half_mirror row_mask:0xf bank_mask:0xf bound_ctrl:1
	s_nop 1
	v_mov_b32_dpp v34, v33 row_ror:8 row_mask:0xf bank_mask:0xf bound_ctrl:1
	s_and_saveexec_b64 s[4:5], vcc
	v_add_f32_e32 v33, v33, v34
	ds_write_b32 v48, v33 offset:72
	s_or_b64 exec, exec, s[4:5]
	v_lshl_add_u32 v33, v113, 2, v131
	ds_read2st64_b32 v[36:37], v33 offset0:2 offset1:3
	ds_read2st64_b32 v[40:41], v33 offset1:1
	s_waitcnt lgkmcnt(1)
	v_max_f32_e32 v33, v37, v37
	v_max_f32_e32 v34, v36, v36
	v_max_f32_e32 v33, v34, v33
	s_waitcnt lgkmcnt(0)
	v_max3_f32 v33, v40, v41, v33
	v_sub_f32_e32 v34, v47, v33
	v_mul_f32_e32 v34, 0x3d800000, v34
	v_sub_f32_e32 v36, v43, v33
	v_mul_f32_e32 v34, 0x3fb8aa3b, v34
	v_exp_f32_e32 v34, v34
	v_mul_f32_e32 v36, 0x3d800000, v36
	v_mul_f32_e32 v36, 0x3fb8aa3b, v36
	v_exp_f32_e32 v36, v36
	v_bfe_u32 v38, v34, 16, 1
	v_add_f32_e32 v37, 0, v34
	v_add3_u32 v34, v34, v38, s77
	ds_write_b16_d16_hi v32, v34 offset:528
	v_add_f32_e32 v34, v36, v37
	v_sub_f32_e32 v37, v39, v33
	v_mul_f32_e32 v37, 0x3d800000, v37
	v_mul_f32_e32 v37, 0x3fb8aa3b, v37
	v_sub_f32_e32 v33, v35, v33
	v_exp_f32_e32 v37, v37
	v_mul_f32_e32 v33, 0x3d800000, v33
	v_mul_f32_e32 v33, 0x3fb8aa3b, v33
	v_exp_f32_e32 v33, v33
	v_bfe_u32 v35, v37, 16, 1
	v_add3_u32 v35, v37, v35, s77
	v_add_f32_e32 v34, v37, v34
	ds_write_b16_d16_hi v32, v35 offset:592
	v_bfe_u32 v35, v33, 16, 1
	v_add_f32_e32 v34, v33, v34
	v_add3_u32 v33, v33, v35, s77
	ds_write_b16_d16_hi v32, v33 offset:624
	v_bfe_u32 v38, v36, 16, 1
	v_add_f32_dpp v33, v34, v34 quad_perm:[1,0,3,2] row_mask:0xf bank_mask:0xf bound_ctrl:1
	v_add3_u32 v36, v36, v38, s77
	ds_write_b16_d16_hi v32, v36 offset:560
	v_add_f32_dpp v33, v33, v33 quad_perm:[2,3,0,1] row_mask:0xf bank_mask:0xf bound_ctrl:1
	s_nop 1
	v_add_f32_dpp v33, v33, v33 row_half_mirror row_mask:0xf bank_mask:0xf bound_ctrl:1
	s_nop 1
	v_mov_b32_dpp v34, v33 row_ror:8 row_mask:0xf bank_mask:0xf bound_ctrl:1
	s_and_saveexec_b64 s[4:5], vcc
	v_add_f32_e32 v33, v33, v34
	ds_write_b32 v48, v33 offset:76
	s_or_b64 exec, exec, s[4:5]
	v_or_b32_e32 v33, 0x11480, v49
	v_or_b32_e32 v34, 0x11580, v49
	v_or_b32_e32 v35, 0x11680, v49
	v_or_b32_e32 v36, 0x11780, v49
	ds_read_b32 v36, v36
	ds_read_b32 v35, v35
	ds_read_b32 v33, v33
	ds_read_b32 v34, v34
	s_waitcnt lgkmcnt(3)
	v_max_f32_e32 v36, v36, v36
	s_waitcnt lgkmcnt(2)
	v_max_f32_e32 v35, v35, v35
	v_max_f32_e32 v35, v35, v36
	s_waitcnt lgkmcnt(0)
	v_max3_f32 v33, v33, v34, v35
	v_sub_f32_e32 v28, v28, v33
	v_mul_f32_e32 v28, 0x3d800000, v28
	v_mul_f32_e32 v28, 0x3fb8aa3b, v28
	v_sub_f32_e32 v24, v24, v33
	v_exp_f32_e32 v28, v28
	v_mul_f32_e32 v24, 0x3d800000, v24
	v_mul_f32_e32 v24, 0x3fb8aa3b, v24
	v_sub_f32_e32 v20, v20, v33
	v_exp_f32_e32 v24, v24
	v_mul_f32_e32 v20, 0x3d800000, v20
	v_mul_f32_e32 v20, 0x3fb8aa3b, v20
	v_sub_f32_e32 v16, v16, v33
	v_bfe_u32 v35, v28, 16, 1
	v_exp_f32_e32 v20, v20
	v_mul_f32_e32 v16, 0x3d800000, v16
	v_add_f32_e32 v34, 0, v28
	v_add3_u32 v28, v28, v35, s77
	v_mul_f32_e32 v16, 0x3fb8aa3b, v16
	ds_write_b16_d16_hi v32, v28 offset:7392
	v_add_f32_e32 v28, v24, v34
	v_bfe_u32 v34, v24, 16, 1
	v_exp_f32_e32 v16, v16
	v_add3_u32 v24, v24, v34, s77
	ds_write_b16_d16_hi v32, v24 offset:7424
	v_add_f32_e32 v24, v20, v28
	v_bfe_u32 v28, v20, 16, 1
	v_add3_u32 v20, v20, v28, s77
	ds_write_b16_d16_hi v32, v20 offset:7456
	v_add_f32_e32 v20, v16, v24
	v_bfe_u32 v24, v16, 16, 1
	v_add3_u32 v16, v16, v24, s77
	ds_write_b16_d16_hi v32, v16 offset:7488
	s_nop 0
	v_add_f32_dpp v16, v20, v20 quad_perm:[1,0,3,2] row_mask:0xf bank_mask:0xf bound_ctrl:1
	s_nop 1
	v_add_f32_dpp v16, v16, v16 quad_perm:[2,3,0,1] row_mask:0xf bank_mask:0xf bound_ctrl:1
	s_nop 1
	v_add_f32_dpp v16, v16, v16 row_half_mirror row_mask:0xf bank_mask:0xf bound_ctrl:1
	s_nop 1
	v_mov_b32_dpp v20, v16 row_ror:8 row_mask:0xf bank_mask:0xf bound_ctrl:1
	s_and_saveexec_b64 s[4:5], vcc
	v_add_f32_e32 v16, v16, v20
	ds_write_b32 v48, v16 offset:128
	s_or_b64 exec, exec, s[4:5]
	v_lshl_add_u32 v16, v113, 2, v132
	ds_read2st64_b32 v[34:35], v16 offset0:2 offset1:3
	ds_read2st64_b32 v[36:37], v16 offset1:1
	s_waitcnt lgkmcnt(1)
	v_max_f32_e32 v16, v35, v35
	v_max_f32_e32 v20, v34, v34
	v_max_f32_e32 v16, v20, v16
	s_waitcnt lgkmcnt(0)
; __device__ __forceinline__ void xattn_item(const Params& p, char* smem, const int tile, const int hm) {
;     ...
; #pragma unroll
;     for (int m = 0; m < 4; ++m)
; #pragma unroll
;       for (int j = 0; j < 4; ++j) {
;         const int row = m * 16 + lq * 4 + j;
;         const float gmx = fmaxf(fmaxf(sMax[row], sMax[64 + row]), fmaxf(sMax[128 + row], sMax[192 + row]));
;         float sum = 0.f;
; #pragma unroll
;         for (int n = 0; n < 4; ++n) {
;           const float e = __expf((acc[m][n][j] - gmx) * 0.0625f);
;           sum += e;
;           sQ[row * 264 + w * 64 + n * 16 + l15] = f2bf(e);
;         }
;         sum = row16_sum(sum);
;         if (l15 == 0) sSum[w * 64 + row] = sum;
;       }
	v_max3_f32 v16, v36, v37, v16
	v_sub_f32_e32 v20, v29, v16
	v_mul_f32_e32 v20, 0x3d800000, v20
	v_sub_f32_e32 v24, v25, v16
	v_mul_f32_e32 v20, 0x3fb8aa3b, v20
	v_sub_f32_e32 v21, v21, v16
	v_exp_f32_e32 v20, v20
	v_mul_f32_e32 v24, 0x3d800000, v24
	v_mul_f32_e32 v21, 0x3d800000, v21
	v_mul_f32_e32 v24, 0x3fb8aa3b, v24
	v_mul_f32_e32 v21, 0x3fb8aa3b, v21
	v_sub_f32_e32 v16, v17, v16
	v_exp_f32_e32 v24, v24
	v_exp_f32_e32 v21, v21
	v_mul_f32_e32 v16, 0x3d800000, v16
	v_mul_f32_e32 v16, 0x3fb8aa3b, v16
	v_bfe_u32 v28, v20, 16, 1
	v_exp_f32_e32 v16, v16
	v_add_f32_e32 v25, 0, v20
	v_add3_u32 v20, v20, v28, s77
	ds_write_b16_d16_hi v32, v20 offset:7920
	v_add_f32_e32 v20, v24, v25
	v_bfe_u32 v17, v21, 16, 1
	v_add_f32_e32 v20, v21, v20
	v_add3_u32 v17, v21, v17, s77
	ds_write_b16_d16_hi v32, v17 offset:7984
	v_add_f32_e32 v17, v16, v20
	v_bfe_u32 v20, v16, 16, 1
	v_add3_u32 v16, v16, v20, s77
	ds_write_b16_d16_hi v32, v16 offset:8016
	v_bfe_u32 v25, v24, 16, 1
	v_add_f32_dpp v16, v17, v17 quad_perm:[1,0,3,2] row_mask:0xf bank_mask:0xf bound_ctrl:1
	v_add3_u32 v24, v24, v25, s77
	ds_write_b16_d16_hi v32, v24 offset:7952
	v_add_f32_dpp v16, v16, v16 quad_perm:[2,3,0,1] row_mask:0xf bank_mask:0xf bound_ctrl:1
	s_nop 1
	v_add_f32_dpp v16, v16, v16 row_half_mirror row_mask:0xf bank_mask:0xf bound_ctrl:1
	s_nop 1
	v_mov_b32_dpp v17, v16 row_ror:8 row_mask:0xf bank_mask:0xf bound_ctrl:1
	s_and_saveexec_b64 s[4:5], vcc
	v_add_f32_e32 v16, v16, v17
	ds_write_b32 v48, v16 offset:132
	s_or_b64 exec, exec, s[4:5]
	v_lshl_add_u32 v20, v113, 2, v133
	ds_read2st64_b32 v[16:17], v20 offset0:2 offset1:3
	ds_read2st64_b32 v[20:21], v20 offset1:1
	s_waitcnt lgkmcnt(1)
	v_max_f32_e32 v17, v17, v17
	v_max_f32_e32 v16, v16, v16
	v_max_f32_e32 v16, v16, v17
	s_waitcnt lgkmcnt(0)
	v_max3_f32 v16, v20, v21, v16
	v_sub_f32_e32 v17, v30, v16
	v_mul_f32_e32 v17, 0x3d800000, v17
	v_sub_f32_e32 v20, v26, v16
	v_mul_f32_e32 v17, 0x3fb8aa3b, v17
	v_exp_f32_e32 v17, v17
	v_mul_f32_e32 v20, 0x3d800000, v20
	v_mul_f32_e32 v20, 0x3fb8aa3b, v20
	v_exp_f32_e32 v20, v20
	v_bfe_u32 v24, v17, 16, 1
	v_add_f32_e32 v21, 0, v17
	v_add3_u32 v17, v17, v24, s77
	ds_write_b16_d16_hi v32, v17 offset:8448
	v_add_f32_e32 v17, v20, v21
	v_sub_f32_e32 v21, v22, v16
	v_mul_f32_e32 v21, 0x3d800000, v21
	v_mul_f32_e32 v21, 0x3fb8aa3b, v21
	v_sub_f32_e32 v16, v18, v16
	v_exp_f32_e32 v21, v21
	v_mul_f32_e32 v16, 0x3d800000, v16
	v_mul_f32_e32 v16, 0x3fb8aa3b, v16
	v_exp_f32_e32 v16, v16
	v_bfe_u32 v18, v21, 16, 1
	v_add3_u32 v18, v21, v18, s77
	v_add_f32_e32 v17, v21, v17
	ds_write_b16_d16_hi v32, v18 offset:8512
	v_bfe_u32 v18, v16, 16, 1
	v_add_f32_e32 v17, v16, v17
	v_add3_u32 v16, v16, v18, s77
	ds_write_b16_d16_hi v32, v16 offset:8544
	v_bfe_u32 v22, v20, 16, 1
	v_add_f32_dpp v16, v17, v17 quad_perm:[1,0,3,2] row_mask:0xf bank_mask:0xf bound_ctrl:1
	v_add3_u32 v20, v20, v22, s77
	ds_write_b16_d16_hi v32, v20 offset:8480
	v_add_f32_dpp v16, v16, v16 quad_perm:[2,3,0,1] row_mask:0xf bank_mask:0xf bound_ctrl:1
	s_nop 1
	v_add_f32_dpp v16, v16, v16 row_half_mirror row_mask:0xf bank_mask:0xf bound_ctrl:1
	s_nop 1
	v_mov_b32_dpp v17, v16 row_ror:8 row_mask:0xf bank_mask:0xf bound_ctrl:1
	s_and_saveexec_b64 s[4:5], vcc
	v_add_f32_e32 v16, v16, v17
	ds_write_b32 v48, v16 offset:136
	s_or_b64 exec, exec, s[4:5]
	v_lshl_add_u32 v18, v113, 2, v134
	ds_read2st64_b32 v[16:17], v18 offset0:2 offset1:3
	ds_read2st64_b32 v[20:21], v18 offset1:1
	s_waitcnt lgkmcnt(1)
	v_max_f32_e32 v17, v17, v17
	v_max_f32_e32 v16, v16, v16
	v_max_f32_e32 v16, v16, v17
	s_waitcnt lgkmcnt(0)
	v_max3_f32 v16, v20, v21, v16
	v_sub_f32_e32 v17, v31, v16
	v_mul_f32_e32 v17, 0x3d800000, v17
	v_sub_f32_e32 v18, v27, v16
	v_mul_f32_e32 v17, 0x3fb8aa3b, v17
	v_exp_f32_e32 v17, v17
	v_mul_f32_e32 v18, 0x3d800000, v18
	v_mul_f32_e32 v18, 0x3fb8aa3b, v18
	v_exp_f32_e32 v18, v18
	v_bfe_u32 v21, v17, 16, 1
	v_add_f32_e32 v20, 0, v17
	v_add3_u32 v17, v17, v21, s77
	ds_write_b16_d16_hi v32, v17 offset:8976
	v_add_f32_e32 v17, v18, v20
	v_sub_f32_e32 v20, v23, v16
	v_mul_f32_e32 v20, 0x3d800000, v20
	v_mul_f32_e32 v20, 0x3fb8aa3b, v20
	v_sub_f32_e32 v16, v19, v16
	v_exp_f32_e32 v20, v20
	v_mul_f32_e32 v16, 0x3d800000, v16
	v_mul_f32_e32 v16, 0x3fb8aa3b, v16
	v_bfe_u32 v21, v18, 16, 1
	v_exp_f32_e32 v16, v16
	v_add3_u32 v18, v18, v21, s77
	ds_write_b16_d16_hi v32, v18 offset:9008
	v_bfe_u32 v18, v20, 16, 1
	v_add3_u32 v18, v20, v18, s77
	v_add_f32_e32 v17, v20, v17
	ds_write_b16_d16_hi v32, v18 offset:9040
	v_bfe_u32 v18, v16, 16, 1
	v_add_f32_e32 v17, v16, v17
	v_add3_u32 v16, v16, v18, s77
	ds_write_b16_d16_hi v32, v16 offset:9072
	s_nop 0
	v_add_f32_dpp v16, v17, v17 quad_perm:[1,0,3,2] row_mask:0xf bank_mask:0xf bound_ctrl:1
	s_nop 1
	v_add_f32_dpp v16, v16, v16 quad_perm:[2,3,0,1] row_mask:0xf bank_mask:0xf bound_ctrl:1
	s_nop 1
	v_add_f32_dpp v16, v16, v16 row_half_mirror row_mask:0xf bank_mask:0xf bound_ctrl:1
	s_nop 1
	v_mov_b32_dpp v17, v16 row_ror:8 row_mask:0xf bank_mask:0xf bound_ctrl:1
	s_and_saveexec_b64 s[4:5], vcc
	v_add_f32_e32 v16, v16, v17
	ds_write_b32 v48, v16 offset:140
	s_or_b64 exec, exec, s[4:5]
	v_or_b32_e32 v16, 0x114c0, v49
	v_or_b32_e32 v17, 0x115c0, v49
	v_or_b32_e32 v18, 0x116c0, v49
	v_or_b32_e32 v19, 0x117c0, v49
	ds_read_b32 v19, v19
	ds_read_b32 v18, v18
	ds_read_b32 v16, v16
	ds_read_b32 v17, v17
	s_waitcnt lgkmcnt(3)
	v_max_f32_e32 v19, v19, v19
	s_waitcnt lgkmcnt(2)
	v_max_f32_e32 v18, v18, v18
	v_max_f32_e32 v18, v18, v19
	s_waitcnt lgkmcnt(0)
; __device__ __forceinline__ void xattn_item(const Params& p, char* smem, const int tile, const int hm) {
;     ...
; #pragma unroll
;     for (int m = 0; m < 4; ++m)
; #pragma unroll
;       for (int j = 0; j < 4; ++j) {
;         const int row = m * 16 + lq * 4 + j;
;         const float gmx = fmaxf(fmaxf(sMax[row], sMax[64 + row]), fmaxf(sMax[128 + row], sMax[192 + row]));
;         float sum = 0.f;
; #pragma unroll
;         for (int n = 0; n < 4; ++n) {
;           const float e = __expf((acc[m][n][j] - gmx) * 0.0625f);
;           sum += e;
;           sQ[row * 264 + w * 64 + n * 16 + l15] = f2bf(e);
;         }
;         sum = row16_sum(sum);
;         if (l15 == 0) sSum[w * 64 + row] = sum;
;       }
	v_max3_f32 v16, v16, v17, v18
	v_sub_f32_e32 v12, v12, v16
	v_mul_f32_e32 v12, 0x3d800000, v12
	v_mul_f32_e32 v12, 0x3fb8aa3b, v12
	v_sub_f32_e32 v8, v8, v16
	v_exp_f32_e32 v12, v12
	v_mul_f32_e32 v8, 0x3d800000, v8
	v_mul_f32_e32 v8, 0x3fb8aa3b, v8
	v_sub_f32_e32 v4, v4, v16
	v_exp_f32_e32 v8, v8
	v_mul_f32_e32 v4, 0x3d800000, v4
	v_mul_f32_e32 v4, 0x3fb8aa3b, v4
	v_sub_f32_e32 v0, v0, v16
	v_bfe_u32 v18, v12, 16, 1
	v_exp_f32_e32 v4, v4
	v_mul_f32_e32 v0, 0x3d800000, v0
	v_add_f32_e32 v17, 0, v12
	v_add3_u32 v12, v12, v18, s77
	v_mul_f32_e32 v0, 0x3fb8aa3b, v0
	ds_write_b16_d16_hi v32, v12 offset:15840
	v_add_f32_e32 v12, v8, v17
	v_bfe_u32 v17, v8, 16, 1
	v_exp_f32_e32 v0, v0
	v_add3_u32 v8, v8, v17, s77
	ds_write_b16_d16_hi v32, v8 offset:15872
	v_add_f32_e32 v8, v4, v12
	v_bfe_u32 v12, v4, 16, 1
	v_add3_u32 v4, v4, v12, s77
	ds_write_b16_d16_hi v32, v4 offset:15904
	v_add_f32_e32 v4, v0, v8
	v_bfe_u32 v8, v0, 16, 1
	v_add3_u32 v0, v0, v8, s77
	ds_write_b16_d16_hi v32, v0 offset:15936
	s_nop 0
	v_add_f32_dpp v0, v4, v4 quad_perm:[1,0,3,2] row_mask:0xf bank_mask:0xf bound_ctrl:1
	s_nop 1
	v_add_f32_dpp v0, v0, v0 quad_perm:[2,3,0,1] row_mask:0xf bank_mask:0xf bound_ctrl:1
	s_nop 1
	v_add_f32_dpp v0, v0, v0 row_half_mirror row_mask:0xf bank_mask:0xf bound_ctrl:1
	s_nop 1
	v_mov_b32_dpp v4, v0 row_ror:8 row_mask:0xf bank_mask:0xf bound_ctrl:1
	s_and_saveexec_b64 s[4:5], vcc
	v_add_f32_e32 v0, v0, v4
	ds_write_b32 v48, v0 offset:192
	s_or_b64 exec, exec, s[4:5]
	v_lshl_add_u32 v0, v113, 2, v135
	ds_read2st64_b32 v[16:17], v0 offset0:2 offset1:3
	ds_read2st64_b32 v[18:19], v0 offset1:1
	s_waitcnt lgkmcnt(1)
	v_max_f32_e32 v0, v17, v17
	v_max_f32_e32 v4, v16, v16
	v_max_f32_e32 v0, v4, v0
	s_waitcnt lgkmcnt(0)
	v_max3_f32 v0, v18, v19, v0
	v_sub_f32_e32 v4, v13, v0
	v_mul_f32_e32 v4, 0x3d800000, v4
	v_sub_f32_e32 v8, v9, v0
	v_mul_f32_e32 v4, 0x3fb8aa3b, v4
	v_sub_f32_e32 v5, v5, v0
	v_exp_f32_e32 v4, v4
	v_mul_f32_e32 v8, 0x3d800000, v8
	v_mul_f32_e32 v5, 0x3d800000, v5
	v_mul_f32_e32 v8, 0x3fb8aa3b, v8
	v_mul_f32_e32 v5, 0x3fb8aa3b, v5
	v_sub_f32_e32 v0, v1, v0
	v_exp_f32_e32 v8, v8
	v_exp_f32_e32 v5, v5
	v_mul_f32_e32 v0, 0x3d800000, v0
	v_mul_f32_e32 v0, 0x3fb8aa3b, v0
	v_bfe_u32 v12, v4, 16, 1
	v_exp_f32_e32 v0, v0
	v_add_f32_e32 v9, 0, v4
	v_add3_u32 v4, v4, v12, s77
	ds_write_b16_d16_hi v32, v4 offset:16368
	v_add_f32_e32 v4, v8, v9
	v_bfe_u32 v1, v5, 16, 1
	v_add_f32_e32 v4, v5, v4
	v_add3_u32 v1, v5, v1, s77
	ds_write_b16_d16_hi v32, v1 offset:16432
	v_add_f32_e32 v1, v0, v4
	v_bfe_u32 v4, v0, 16, 1
	v_add3_u32 v0, v0, v4, s77
	ds_write_b16_d16_hi v32, v0 offset:16464
	v_bfe_u32 v9, v8, 16, 1
	v_add_f32_dpp v0, v1, v1 quad_perm:[1,0,3,2] row_mask:0xf bank_mask:0xf bound_ctrl:1
	v_add3_u32 v8, v8, v9, s77
	ds_write_b16_d16_hi v32, v8 offset:16400
	v_add_f32_dpp v0, v0, v0 quad_perm:[2,3,0,1] row_mask:0xf bank_mask:0xf bound_ctrl:1
	s_nop 1
	v_add_f32_dpp v0, v0, v0 row_half_mirror row_mask:0xf bank_mask:0xf bound_ctrl:1
	s_nop 1
	v_mov_b32_dpp v1, v0 row_ror:8 row_mask:0xf bank_mask:0xf bound_ctrl:1
	s_and_saveexec_b64 s[4:5], vcc
	v_add_f32_e32 v0, v0, v1
	ds_write_b32 v48, v0 offset:196
	s_or_b64 exec, exec, s[4:5]
	v_lshl_add_u32 v4, v113, 2, v136
	ds_read2st64_b32 v[0:1], v4 offset0:2 offset1:3
	ds_read2st64_b32 v[4:5], v4 offset1:1
	s_waitcnt lgkmcnt(1)
	v_max_f32_e32 v1, v1, v1
	v_max_f32_e32 v0, v0, v0
	v_max_f32_e32 v0, v0, v1
	s_waitcnt lgkmcnt(0)
	v_max3_f32 v0, v4, v5, v0
	v_sub_f32_e32 v1, v14, v0
	v_mul_f32_e32 v1, 0x3d800000, v1
	v_sub_f32_e32 v4, v10, v0
	v_mul_f32_e32 v1, 0x3fb8aa3b, v1
	v_exp_f32_e32 v1, v1
	v_mul_f32_e32 v4, 0x3d800000, v4
	v_mul_f32_e32 v4, 0x3fb8aa3b, v4
	v_exp_f32_e32 v4, v4
	v_bfe_u32 v8, v1, 16, 1
	v_add_f32_e32 v5, 0, v1
	v_add3_u32 v1, v1, v8, s77
	ds_write_b16_d16_hi v32, v1 offset:16896
	v_add_f32_e32 v1, v4, v5
	v_sub_f32_e32 v5, v6, v0
	v_mul_f32_e32 v5, 0x3d800000, v5
	v_mul_f32_e32 v5, 0x3fb8aa3b, v5
	v_sub_f32_e32 v0, v2, v0
	v_exp_f32_e32 v5, v5
	v_mul_f32_e32 v0, 0x3d800000, v0
	v_mul_f32_e32 v0, 0x3fb8aa3b, v0
	v_exp_f32_e32 v0, v0
	v_bfe_u32 v2, v5, 16, 1
	v_add3_u32 v2, v5, v2, s77
	v_add_f32_e32 v1, v5, v1
	ds_write_b16_d16_hi v32, v2 offset:16960
	v_bfe_u32 v2, v0, 16, 1
	v_add_f32_e32 v1, v0, v1
	v_add3_u32 v0, v0, v2, s77
	ds_write_b16_d16_hi v32, v0 offset:16992
	v_bfe_u32 v6, v4, 16, 1
	v_add_f32_dpp v0, v1, v1 quad_perm:[1,0,3,2] row_mask:0xf bank_mask:0xf bound_ctrl:1
	v_add3_u32 v4, v4, v6, s77
	ds_write_b16_d16_hi v32, v4 offset:16928
	v_add_f32_dpp v0, v0, v0 quad_perm:[2,3,0,1] row_mask:0xf bank_mask:0xf bound_ctrl:1
	s_nop 1
	v_add_f32_dpp v0, v0, v0 row_half_mirror row_mask:0xf bank_mask:0xf bound_ctrl:1
	s_nop 1
	v_mov_b32_dpp v1, v0 row_ror:8 row_mask:0xf bank_mask:0xf bound_ctrl:1
	s_and_saveexec_b64 s[4:5], vcc
	v_add_f32_e32 v0, v0, v1
	ds_write_b32 v48, v0 offset:200
	s_or_b64 exec, exec, s[4:5]
	v_lshl_add_u32 v2, v113, 2, v137
	ds_read2st64_b32 v[0:1], v2 offset0:2 offset1:3
	ds_read2st64_b32 v[4:5], v2 offset1:1
	s_waitcnt lgkmcnt(1)
	v_max_f32_e32 v1, v1, v1
	v_max_f32_e32 v0, v0, v0
	v_max_f32_e32 v0, v0, v1
	s_waitcnt lgkmcnt(0)
; #define MFMA(a, b, c) __builtin_amdgcn_mfma_f32_16x16x32_bf16((a), (b), (c), 0, 0, 0)
; __device__ __forceinline__ void xattn_item(const Params& p, char* smem, const int tile, const int hm) {
;     ...
;         if (l15 == 0) sSum[w * 64 + row] = sum;
;       }
; #pragma unroll
;     for (int m = 0; m < 4; ++m)
; #pragma unroll
;       for (int n = 0; n < 4; ++n) acc[m][n] = f32x4{0.f, 0.f, 0.f, 0.f};
;     for (int kt = 0; kt < 4; ++kt) {
; #pragma unroll
;       for (int i = 0; i < 8; ++i) {
;         const int c = tid + 256 * i, row = c >> 3, cc = c & 7;
;         st[i] = *(const u32x4*)(vtm + (size_t)(b * 1024 + hm * 256 + row) * 256 + kt * 64 + cc * 8);
;       }
;       __syncthreads();
; #pragma unroll
;       for (int i = 0; i < 8; ++i) {
;         const int c = tid + 256 * i, row = c >> 3, cc = c & 7;
;         *(u32x4*)(sT + row * 72 + cc * 8) = st[i];
;       }
;       __syncthreads();
; #pragma unroll
;       for (int ks = 0; ks < 2; ++ks) {
;         bf16x8 pf[4], vf[4];
; #pragma unroll
;         for (int m = 0; m < 4; ++m) pf[m] = *(const bf16x8*)(sQ + (m * 16 + l15) * 264 + kt * 64 + ks * 32 + lq * 8);
; #pragma unroll
;         for (int n = 0; n < 4; ++n) vf[n] = *(const bf16x8*)(sT + (w * 64 + n * 16 + l15) * 72 + ks * 32 + lq * 8);
; #pragma unroll
;         for (int m = 0; m < 4; ++m)
; #pragma unroll
;           for (int n = 0; n < 4; ++n) acc[m][n] = MFMA(vf[n], pf[m], acc[m][n]);
;       }
	v_max3_f32 v0, v4, v5, v0
	v_sub_f32_e32 v1, v15, v0
	v_mul_f32_e32 v1, 0x3d800000, v1
	v_sub_f32_e32 v2, v11, v0
	v_mul_f32_e32 v1, 0x3fb8aa3b, v1
	v_exp_f32_e32 v1, v1
	v_mul_f32_e32 v2, 0x3d800000, v2
	v_mul_f32_e32 v2, 0x3fb8aa3b, v2
	v_exp_f32_e32 v2, v2
	v_bfe_u32 v5, v1, 16, 1
	v_add_f32_e32 v4, 0, v1
	v_add3_u32 v1, v1, v5, s77
	ds_write_b16_d16_hi v32, v1 offset:17424
	v_add_f32_e32 v1, v2, v4
	v_sub_f32_e32 v4, v7, v0
	v_mul_f32_e32 v4, 0x3d800000, v4
	v_mul_f32_e32 v4, 0x3fb8aa3b, v4
	v_sub_f32_e32 v0, v3, v0
	v_exp_f32_e32 v4, v4
	v_mul_f32_e32 v0, 0x3d800000, v0
	v_mul_f32_e32 v0, 0x3fb8aa3b, v0
	v_bfe_u32 v5, v2, 16, 1
	v_exp_f32_e32 v0, v0
	v_add3_u32 v2, v2, v5, s77
	ds_write_b16_d16_hi v32, v2 offset:17456
	v_bfe_u32 v2, v4, 16, 1
	v_add3_u32 v2, v4, v2, s77
	v_add_f32_e32 v1, v4, v1
	ds_write_b16_d16_hi v32, v2 offset:17488
	v_bfe_u32 v2, v0, 16, 1
	v_add_f32_e32 v1, v0, v1
	v_add3_u32 v0, v0, v2, s77
	ds_write_b16_d16_hi v32, v0 offset:17520
	s_nop 0
	v_add_f32_dpp v0, v1, v1 quad_perm:[1,0,3,2] row_mask:0xf bank_mask:0xf bound_ctrl:1
	s_nop 1
	v_add_f32_dpp v0, v0, v0 quad_perm:[2,3,0,1] row_mask:0xf bank_mask:0xf bound_ctrl:1
	s_nop 1
	v_add_f32_dpp v0, v0, v0 row_half_mirror row_mask:0xf bank_mask:0xf bound_ctrl:1
	s_nop 1
	v_mov_b32_dpp v1, v0 row_ror:8 row_mask:0xf bank_mask:0xf bound_ctrl:1
	s_and_saveexec_b64 s[4:5], vcc
	v_add_f32_e32 v0, v0, v1
	ds_write_b32 v48, v0 offset:204
	s_or_b64 exec, exec, s[4:5]
	s_lshl_b32 s4, s42, 10
	s_or_b32 s4, s4, s41
	v_add_u32_e32 v0, s4, v65
	v_add_u32_e32 v8, s4, v67
	v_add_u32_e32 v16, s4, v69
	v_add_u32_e32 v26, s4, v71
	v_ashrrev_i32_e32 v1, 31, v0
	v_ashrrev_i32_e32 v9, 31, v8
	v_ashrrev_i32_e32 v17, 31, v16
	v_ashrrev_i32_e32 v27, 31, v26
	v_lshl_add_u64 v[24:25], s[28:29], 0, v[100:101]
	v_lshlrev_b64 v[0:1], 9, v[0:1]
	v_lshlrev_b64 v[8:9], 9, v[8:9]
	v_lshlrev_b64 v[16:17], 9, v[16:17]
	v_lshlrev_b64 v[26:27], 9, v[26:27]
	v_lshl_add_u64 v[28:29], v[24:25], 0, v[0:1]
	v_add_u32_e32 v0, s4, v66
	v_lshl_add_u64 v[32:33], v[24:25], 0, v[8:9]
	v_add_u32_e32 v8, s4, v68
	v_lshl_add_u64 v[36:37], v[24:25], 0, v[16:17]
	v_add_u32_e32 v16, s4, v70
	v_lshl_add_u64 v[68:69], v[24:25], 0, v[26:27]
	v_add_u32_e32 v26, s4, v72
	v_ashrrev_i32_e32 v1, 31, v0
	v_ashrrev_i32_e32 v9, 31, v8
	v_ashrrev_i32_e32 v17, 31, v16
	v_ashrrev_i32_e32 v27, 31, v26
	v_lshlrev_b64 v[0:1], 9, v[0:1]
	v_lshlrev_b64 v[8:9], 9, v[8:9]
	v_lshlrev_b64 v[16:17], 9, v[16:17]
	v_lshlrev_b64 v[26:27], 9, v[26:27]
	v_lshl_add_u64 v[30:31], v[24:25], 0, v[0:1]
	v_lshl_add_u64 v[34:35], v[24:25], 0, v[8:9]
	v_lshl_add_u64 v[38:39], v[24:25], 0, v[16:17]
	v_lshl_add_u64 v[70:71], v[24:25], 0, v[26:27]
	s_waitcnt vmcnt(0) lgkmcnt(0)
	s_barrier
	v_lshrrev_b32_e32 v254, 6, v197
	v_and_b32_e32 v255, 15, v197
	v_lshl_add_u32 v254, v254, 6, v255
	v_bfe_u32 v255, v197, 4, 2
	v_lshlrev_b32_e32 v254, 9, v254
	v_lshl_add_u32 v252, v255, 4, v254
	v_add_u32_e32 v253, 0x4000, v252
	s_lshl_b32 s100, s42, 10
	s_or_b32 s100, s100, s41
	s_lshl_b32 s100, s100, 9
	s_add_u32 s96, s28, s100
	s_addc_u32 s97, s29, 0
	s_add_u32 s98, s96, 0x2000
	s_addc_u32 s99, s97, 0
	s_add_u32 s4, s14, s40
	v_or_b32_e32 v126, 16, v112
	v_ashrrev_i32_e32 v97, 31, v96
	v_lshlrev_b32_e32 v100, 1, v113
	v_lshlrev_b32_e32 v113, 2, v112
	s_addc_u32 s5, s15, 0
	v_or_b32_e32 v127, 0x11800, v113
	v_or_b32_e32 v128, 0x11900, v113
	v_or_b32_e32 v129, 0x11a00, v113
	v_lshlrev_b32_e32 v117, 2, v126
	v_or_b32_e32 v208, 0x11b00, v113
	v_or_b32_e32 v115, 32, v112
	v_or_b32_e32 v114, 48, v112
	s_waitcnt vmcnt(0) lgkmcnt(0)
	global_load_dwordx4 v[0:3], v252, s[96:97]
	v_mul_u32_u24_e32 v4, 0x210, v112
	v_add_u32_e32 v116, v64, v4
	ds_read_b128 v[4:7], v116
	ds_read_b128 v[8:11], v116 offset:64
	global_load_dwordx4 v[12:15], v252, s[96:97] offset:64
	global_load_dwordx4 v[20:23], v252, s[98:99]
	global_load_dwordx4 v[24:27], v252, s[98:99] offset:64
	global_load_dwordx4 v[44:47], v253, s[96:97]
	global_load_dwordx4 v[48:51], v253, s[96:97] offset:64
	global_load_dwordx4 v[56:59], v253, s[98:99]
	global_load_dwordx4 v[60:63], v253, s[98:99] offset:64
	ds_read_b128 v[64:67], v116 offset:8448
	ds_read_b128 v[72:75], v116 offset:8512
	ds_read_b128 v[88:91], v116 offset:16896
	ds_read_b128 v[92:95], v116 offset:16960
	ds_read_b128 v[152:155], v116 offset:25344
	ds_read_b128 v[156:159], v116 offset:25408
	s_waitcnt vmcnt(0) lgkmcnt(0)
	v_mfma_f32_16x16x32_bf16 v[16:19], v[0:3], v[4:7], 0
	v_or_b32_e32 v112, s6, v112
	v_ashrrev_i32_e32 v113, 31, v112
	v_lshlrev_b64 v[112:113], 11, v[112:113]
	s_waitcnt vmcnt(0) lgkmcnt(0)
	v_mfma_f32_16x16x32_bf16 v[40:43], v[20:23], v[4:7], 0
	s_waitcnt vmcnt(0) lgkmcnt(0)
	v_mfma_f32_16x16x32_bf16 v[52:55], v[44:47], v[4:7], 0
	s_waitcnt vmcnt(0) lgkmcnt(0)
	v_mfma_f32_16x16x32_bf16 v[4:7], v[56:59], v[4:7], 0
	s_waitcnt vmcnt(0) lgkmcnt(0)
	v_mfma_f32_16x16x32_bf16 v[76:79], v[0:3], v[64:67], 0
	v_mfma_f32_16x16x32_bf16 v[80:83], v[20:23], v[64:67], 0
	v_mfma_f32_16x16x32_bf16 v[84:87], v[44:47], v[64:67], 0
	v_mfma_f32_16x16x32_bf16 v[64:67], v[56:59], v[64:67], 0
	s_waitcnt vmcnt(0) lgkmcnt(0)
	v_mfma_f32_16x16x32_bf16 v[140:143], v[0:3], v[88:91], 0
	v_mfma_f32_16x16x32_bf16 v[144:147], v[20:23], v[88:91], 0
	v_mfma_f32_16x16x32_bf16 v[148:151], v[44:47], v[88:91], 0
	v_mfma_f32_16x16x32_bf16 v[88:91], v[56:59], v[88:91], 0
	s_waitcnt vmcnt(0) lgkmcnt(0)
; #define MFMA(a, b, c) __builtin_amdgcn_mfma_f32_16x16x32_bf16((a), (b), (c), 0, 0, 0)
; __device__ __forceinline__ void xattn_item(const Params& p, char* smem, const int tile, const int hm) {
;     ...
;     for (int kt = 0; kt < 4; ++kt) {
; #pragma unroll
;       for (int i = 0; i < 8; ++i) {
;         const int c = tid + 256 * i, row = c >> 3, cc = c & 7;
;         st[i] = *(const u32x4*)(vtm + (size_t)(b * 1024 + hm * 256 + row) * 256 + kt * 64 + cc * 8);
;       }
;       __syncthreads();
; #pragma unroll
;       for (int i = 0; i < 8; ++i) {
;         const int c = tid + 256 * i, row = c >> 3, cc = c & 7;
;         *(u32x4*)(sT + row * 72 + cc * 8) = st[i];
;       }
;       __syncthreads();
; #pragma unroll
;       for (int ks = 0; ks < 2; ++ks) {
;         bf16x8 pf[4], vf[4];
; #pragma unroll
;         for (int m = 0; m < 4; ++m) pf[m] = *(const bf16x8*)(sQ + (m * 16 + l15) * 264 + kt * 64 + ks * 32 + lq * 8);
; #pragma unroll
;         for (int n = 0; n < 4; ++n) vf[n] = *(const bf16x8*)(sT + (w * 64 + n * 16 + l15) * 72 + ks * 32 + lq * 8);
; #pragma unroll
;         for (int m = 0; m < 4; ++m)
; #pragma unroll
;           for (int n = 0; n < 4; ++n) acc[m][n] = MFMA(vf[n], pf[m], acc[m][n]);
;       }
	v_mfma_f32_16x16x32_bf16 v[0:3], v[0:3], v[152:155], 0
	v_mfma_f32_16x16x32_bf16 v[20:23], v[20:23], v[152:155], 0
	v_mfma_f32_16x16x32_bf16 v[44:47], v[44:47], v[152:155], 0
	v_mfma_f32_16x16x32_bf16 v[56:59], v[56:59], v[152:155], 0
	v_mfma_f32_16x16x32_bf16 v[16:19], v[12:15], v[8:11], v[16:19]
	v_mfma_f32_16x16x32_bf16 v[40:43], v[24:27], v[8:11], v[40:43]
	v_mfma_f32_16x16x32_bf16 v[52:55], v[48:51], v[8:11], v[52:55]
	v_mfma_f32_16x16x32_bf16 v[4:7], v[60:63], v[8:11], v[4:7]
	v_mfma_f32_16x16x32_bf16 v[8:11], v[12:15], v[72:75], v[76:79]
	v_mfma_f32_16x16x32_bf16 v[76:79], v[24:27], v[72:75], v[80:83]
	v_mfma_f32_16x16x32_bf16 v[80:83], v[48:51], v[72:75], v[84:87]
	v_mfma_f32_16x16x32_bf16 v[64:67], v[60:63], v[72:75], v[64:67]
	v_mfma_f32_16x16x32_bf16 v[72:75], v[12:15], v[92:95], v[140:143]
	v_mfma_f32_16x16x32_bf16 v[84:87], v[24:27], v[92:95], v[144:147]
	v_mfma_f32_16x16x32_bf16 v[140:143], v[48:51], v[92:95], v[148:151]
	s_nop 1
	v_mfma_f32_16x16x32_bf16 v[88:91], v[60:63], v[92:95], v[88:91]
	s_waitcnt vmcnt(0) lgkmcnt(0)
	v_mfma_f32_16x16x32_bf16 v[0:3], v[12:15], v[156:159], v[0:3]
	s_waitcnt vmcnt(0) lgkmcnt(0)
	global_load_dwordx4 v[12:15], v252, s[96:97] offset:128
	v_mfma_f32_16x16x32_bf16 v[20:23], v[24:27], v[156:159], v[20:23]
	v_mfma_f32_16x16x32_bf16 v[24:27], v[48:51], v[156:159], v[44:47]
	v_mfma_f32_16x16x32_bf16 v[44:47], v[60:63], v[156:159], v[56:59]
	ds_read_b128 v[48:51], v116 offset:128
	s_nop 1
	ds_read_b128 v[56:59], v116 offset:192
	global_load_dwordx4 v[60:63], v252, s[96:97] offset:192
	global_load_dwordx4 v[92:95], v252, s[98:99] offset:128
	global_load_dwordx4 v[144:147], v252, s[98:99] offset:192
	global_load_dwordx4 v[148:151], v253, s[96:97] offset:128
	global_load_dwordx4 v[152:155], v253, s[96:97] offset:192
	global_load_dwordx4 v[156:159], v253, s[98:99] offset:128
	global_load_dwordx4 v[160:163], v253, s[98:99] offset:192
	s_waitcnt vmcnt(0) lgkmcnt(0)
	v_mfma_f32_16x16x32_bf16 v[16:19], v[12:15], v[48:51], v[16:19]
	s_waitcnt vmcnt(0) lgkmcnt(0)
	v_mfma_f32_16x16x32_bf16 v[40:43], v[92:95], v[48:51], v[40:43]
	s_waitcnt vmcnt(0) lgkmcnt(0)
	v_mfma_f32_16x16x32_bf16 v[52:55], v[148:151], v[48:51], v[52:55]
	s_waitcnt vmcnt(0) lgkmcnt(0)
	v_mfma_f32_16x16x32_bf16 v[4:7], v[156:159], v[48:51], v[4:7]
	ds_read_b128 v[48:51], v116 offset:8576
	ds_read_b128 v[164:167], v116 offset:8640
	s_waitcnt vmcnt(0) lgkmcnt(0)
	v_mfma_f32_16x16x32_bf16 v[8:11], v[12:15], v[48:51], v[8:11]
	v_mfma_f32_16x16x32_bf16 v[76:79], v[92:95], v[48:51], v[76:79]
	v_mfma_f32_16x16x32_bf16 v[80:83], v[148:151], v[48:51], v[80:83]
	v_mfma_f32_16x16x32_bf16 v[48:51], v[156:159], v[48:51], v[64:67]
	s_nop 2
	ds_read_b128 v[64:67], v116 offset:17024
	ds_read_b128 v[168:171], v116 offset:17088
	s_waitcnt vmcnt(0) lgkmcnt(0)
	v_mfma_f32_16x16x32_bf16 v[72:75], v[12:15], v[64:67], v[72:75]
	v_mfma_f32_16x16x32_bf16 v[84:87], v[92:95], v[64:67], v[84:87]
	v_mfma_f32_16x16x32_bf16 v[140:143], v[148:151], v[64:67], v[140:143]
	v_mfma_f32_16x16x32_bf16 v[64:67], v[156:159], v[64:67], v[88:91]
	s_nop 2
	ds_read_b128 v[88:91], v116 offset:25472
	ds_read_b128 v[172:175], v116 offset:25536
	s_waitcnt vmcnt(0) lgkmcnt(0)
	v_mfma_f32_16x16x32_bf16 v[0:3], v[12:15], v[88:91], v[0:3]
	v_mfma_f32_16x16x32_bf16 v[12:15], v[92:95], v[88:91], v[20:23]
	v_mfma_f32_16x16x32_bf16 v[20:23], v[148:151], v[88:91], v[24:27]
	v_mfma_f32_16x16x32_bf16 v[24:27], v[156:159], v[88:91], v[44:47]
	v_mfma_f32_16x16x32_bf16 v[16:19], v[60:63], v[56:59], v[16:19]
	v_mfma_f32_16x16x32_bf16 v[40:43], v[144:147], v[56:59], v[40:43]
	v_mfma_f32_16x16x32_bf16 v[44:47], v[152:155], v[56:59], v[52:55]
	v_mfma_f32_16x16x32_bf16 v[148:151], v[160:163], v[56:59], v[4:7]
	v_mfma_f32_16x16x32_bf16 v[156:159], v[60:63], v[164:167], v[8:11]
	s_nop 1
	v_mfma_f32_16x16x32_bf16 v[176:179], v[144:147], v[164:167], v[76:79]
	v_mfma_f32_16x16x32_bf16 v[80:83], v[152:155], v[164:167], v[80:83]
	v_mfma_f32_16x16x32_bf16 v[164:167], v[160:163], v[164:167], v[48:51]
	v_mfma_f32_16x16x32_bf16 v[180:183], v[60:63], v[168:171], v[72:75]
	s_nop 1
	v_mfma_f32_16x16x32_bf16 v[184:187], v[144:147], v[168:171], v[84:87]
	s_nop 2
	s_waitcnt vmcnt(0) lgkmcnt(0)
	s_waitcnt vmcnt(0) lgkmcnt(0)
	global_load_dwordx4 v[72:75], v252, s[96:97] offset:256
	v_mfma_f32_16x16x32_bf16 v[140:143], v[152:155], v[168:171], v[140:143]
	v_mfma_f32_16x16x32_bf16 v[168:171], v[160:163], v[168:171], v[64:67]
	v_mfma_f32_16x16x32_bf16 v[52:55], v[60:63], v[172:175], v[0:3]
	v_mfma_f32_16x16x32_bf16 v[64:67], v[144:147], v[172:175], v[12:15]
	v_mfma_f32_16x16x32_bf16 v[56:59], v[152:155], v[172:175], v[20:23]
	v_mfma_f32_16x16x32_bf16 v[60:63], v[160:163], v[172:175], v[24:27]
	s_nop 2
	ds_read_b128 v[24:27], v116 offset:256
	ds_read_b128 v[20:23], v116 offset:320
	global_load_dwordx4 v[12:15], v252, s[96:97] offset:320
	global_load_dwordx4 v[92:95], v252, s[98:99] offset:256
	global_load_dwordx4 v[8:11], v252, s[98:99] offset:320
	global_load_dwordx4 v[88:91], v253, s[96:97] offset:256
	global_load_dwordx4 v[0:3], v253, s[96:97] offset:320
	global_load_dwordx4 v[84:87], v253, s[98:99] offset:256
	ds_read_b128 v[144:147], v116 offset:8704
	global_load_dwordx4 v[4:7], v253, s[98:99] offset:320
	s_waitcnt vmcnt(0) lgkmcnt(0)
	v_mfma_f32_16x16x32_bf16 v[76:79], v[72:75], v[24:27], v[16:19]
	s_waitcnt vmcnt(0) lgkmcnt(0)
	v_mfma_f32_16x16x32_bf16 v[48:51], v[92:95], v[24:27], v[40:43]
	s_nop 0
	ds_read_b128 v[16:19], v116 offset:8768
	s_waitcnt vmcnt(0) lgkmcnt(0)
	v_mfma_f32_16x16x32_bf16 v[40:43], v[88:91], v[24:27], v[44:47]
	s_waitcnt vmcnt(0) lgkmcnt(0)
; __device__ __forceinline__ unsigned pack2(float a, float b) { return (unsigned)f2bf(a) | ((unsigned)f2bf(b) << 16); }
; #define MFMA(a, b, c) __builtin_amdgcn_mfma_f32_16x16x32_bf16((a), (b), (c), 0, 0, 0)
; __device__ __forceinline__ void xattn_item(const Params& p, char* smem, const int tile, const int hm) {
;     ...
;       for (int ks = 0; ks < 2; ++ks) {
;         bf16x8 pf[4], vf[4];
; #pragma unroll
;         for (int m = 0; m < 4; ++m) pf[m] = *(const bf16x8*)(sQ + (m * 16 + l15) * 264 + kt * 64 + ks * 32 + lq * 8);
; #pragma unroll
;         for (int n = 0; n < 4; ++n) vf[n] = *(const bf16x8*)(sT + (w * 64 + n * 16 + l15) * 72 + ks * 32 + lq * 8);
; #pragma unroll
;         for (int m = 0; m < 4; ++m)
; #pragma unroll
;           for (int n = 0; n < 4; ++n) acc[m][n] = MFMA(vf[n], pf[m], acc[m][n]);
;       }
;     }
; #pragma unroll
;     for (int m = 0; m < 4; ++m) {
;       const int row = m * 16 + l15;
;       const float inv = 1.f / (sSum[row] + sSum[64 + row] + sSum[128 + row] + sSum[192 + row]);
; #pragma unroll
;       for (int n = 0; n < 4; ++n)
;         *(uint2*)(xo + (size_t)(tok0 + row) * 1024 + hm * 256 + w * 64 + n * 16 + lq * 4) =
;             make_uint2(pack2(acc[m][n][0] * inv, acc[m][n][1] * inv), pack2(acc[m][n][2] * inv, acc[m][n][3] * inv));
;     }
	v_mfma_f32_16x16x32_bf16 v[24:27], v[84:87], v[24:27], v[148:151]
	s_nop 2
	s_waitcnt vmcnt(0) lgkmcnt(0)
	v_mfma_f32_16x16x32_bf16 v[44:47], v[72:75], v[144:147], v[156:159]
	s_nop 2
	v_mfma_f32_16x16x32_bf16 v[36:39], v[92:95], v[144:147], v[176:179]
	s_nop 2
	ds_read_b128 v[202:205], v116 offset:17152
	ds_read_b128 v[68:71], v116 offset:17216
	v_mfma_f32_16x16x32_bf16 v[32:35], v[84:87], v[144:147], v[164:167]
	s_nop 2
	ds_read_b128 v[164:167], v116 offset:25600
	v_mfma_f32_16x16x32_bf16 v[28:31], v[88:91], v[144:147], v[80:83]
	s_waitcnt vmcnt(0) lgkmcnt(0)
	v_mfma_f32_16x16x32_bf16 v[80:83], v[72:75], v[202:205], v[180:183]
	s_nop 2
	ds_read_b128 v[180:183], v116 offset:25664
	s_waitcnt vmcnt(0) lgkmcnt(0)
	v_mfma_f32_16x16x32_bf16 v[72:75], v[72:75], v[164:167], v[52:55]
	s_waitcnt vmcnt(0) lgkmcnt(0)
	s_nop 0
	v_lshl_add_u64 v[52:53], v[96:97], 1, s[4:5]
	v_mfma_f32_16x16x32_bf16 v[144:147], v[92:95], v[202:205], v[184:187]
	v_lshl_add_u64 v[52:53], v[52:53], 0, v[100:101]
	v_mfma_f32_16x16x32_bf16 v[140:143], v[88:91], v[202:205], v[140:143]
	s_waitcnt vmcnt(0) lgkmcnt(0)
	v_mfma_f32_16x16x32_bf16 v[168:171], v[84:87], v[202:205], v[168:171]
	v_or_b32_e32 v202, 0x11800, v117
	v_or_b32_e32 v203, 0x11900, v117
	v_or_b32_e32 v204, 0x11a00, v117
	v_mfma_f32_16x16x32_bf16 v[64:67], v[92:95], v[164:167], v[64:67]
	v_or_b32_e32 v205, 0x11b00, v117
	v_lshl_add_u64 v[112:113], v[52:53], 0, v[112:113]
	v_mfma_f32_16x16x32_bf16 v[54:57], v[88:91], v[164:167], v[56:59]
	v_mfma_f32_16x16x32_bf16 v[58:61], v[84:87], v[164:167], v[60:63]
	ds_read_b128 v[84:87], v116 offset:384
	ds_read_b128 v[88:91], v116 offset:448
	ds_read_b128 v[92:95], v116 offset:8832
	ds_read_b128 v[96:99], v116 offset:8896
	ds_read_b128 v[148:151], v116 offset:17280
	ds_read_b128 v[152:155], v116 offset:17344
	ds_read_b128 v[156:159], v116 offset:25728
	ds_read_b128 v[116:119], v116 offset:25792
	global_load_dwordx4 v[160:163], v252, s[96:97] offset:384
	global_load_dwordx4 v[164:167], v252, s[96:97] offset:448
	global_load_dwordx4 v[172:175], v252, s[98:99] offset:384
	global_load_dwordx4 v[176:179], v252, s[98:99] offset:448
	global_load_dwordx4 v[184:187], v253, s[96:97] offset:384
	global_load_dwordx4 v[104:107], v253, s[96:97] offset:448
	global_load_dwordx4 v[188:191], v253, s[98:99] offset:384
	global_load_dwordx4 v[108:111], v253, s[98:99] offset:448
	ds_read_b32 v62, v127
	ds_read_b32 v63, v128
	ds_read_b32 v100, v129
	ds_read_b32 v127, v208
	ds_read_b32 v128, v202
	ds_read_b32 v129, v203
	ds_read_b32 v198, v204
	ds_read_b32 v199, v205
	s_waitcnt vmcnt(0) lgkmcnt(0)
	v_add_f32_e32 v62, v62, v63
	v_mfma_f32_16x16x32_bf16 v[76:79], v[12:15], v[20:23], v[76:79]
	s_waitcnt vmcnt(0) lgkmcnt(0)
	v_add_f32_e32 v62, v62, v100
	s_waitcnt vmcnt(0) lgkmcnt(0)
	v_add_f32_e32 v100, v62, v127
	v_div_scale_f32 v127, s[4:5], v100, v100, 1.0
	v_mfma_f32_16x16x32_bf16 v[48:51], v[8:11], v[20:23], v[48:51]
	v_rcp_f32_e32 v200, v127
	v_div_scale_f32 v201, vcc, 1.0, v100, 1.0
	v_mfma_f32_16x16x32_bf16 v[76:79], v[160:163], v[84:87], v[76:79]
	v_fma_f32 v62, -v127, v200, 1.0
	v_fmac_f32_e32 v200, v62, v200
	v_mul_f32_e32 v202, v201, v200
	v_mfma_f32_16x16x32_bf16 v[48:51], v[172:175], v[84:87], v[48:51]
	v_fma_f32 v62, -v127, v202, v201
	v_fmac_f32_e32 v202, v62, v200
	v_mfma_f32_16x16x32_bf16 v[76:79], v[164:167], v[88:91], v[76:79]
	v_mfma_f32_16x16x32_bf16 v[48:51], v[176:179], v[88:91], v[48:51]
	v_mfma_f32_16x16x32_bf16 v[40:43], v[0:3], v[20:23], v[40:43]
	s_nop 5
	v_mov_b32_e32 v62, v76
	v_mov_b32_e32 v76, v48
	v_fma_f32 v48, -v127, v202, v201
	v_div_fmas_f32 v48, v48, v200, v202
	v_mov_b32_e32 v63, v78
	v_mov_b32_e32 v78, v77
	v_div_fixup_f32 v48, v48, v100, 1.0
	v_mov_b32_e32 v77, v50
	v_mov_b32_e32 v50, v49
	v_pk_mul_f32 v[62:63], v[62:63], v[48:49] op_sel_hi:[1,0]
	v_pk_mul_f32 v[78:79], v[78:79], v[48:49] op_sel_hi:[1,0]
	v_pk_mul_f32 v[76:77], v[76:77], v[48:49] op_sel_hi:[1,0]
	v_pk_mul_f32 v[50:51], v[50:51], v[48:49] op_sel_hi:[1,0]
	v_and_b32_sdwa v49, v63, v120 dst_sel:DWORD dst_unused:UNUSED_PAD src0_sel:WORD_1 src1_sel:DWORD
	v_and_b32_sdwa v127, v79, v120 dst_sel:DWORD dst_unused:UNUSED_PAD src0_sel:WORD_1 src1_sel:DWORD
	v_and_b32_sdwa v200, v78, v120 dst_sel:DWORD dst_unused:UNUSED_PAD src0_sel:WORD_1 src1_sel:DWORD
	v_mfma_f32_16x16x32_bf16 v[20:23], v[4:7], v[20:23], v[24:27]
	v_and_b32_sdwa v100, v62, v120 dst_sel:DWORD dst_unused:UNUSED_PAD src0_sel:WORD_1 src1_sel:DWORD
	v_add3_u32 v49, v63, v49, s77
	v_add3_u32 v63, v79, v127, s77
	v_mfma_f32_16x16x32_bf16 v[40:43], v[184:187], v[84:87], v[40:43]
	v_add3_u32 v78, v78, v200, s77
	v_add3_u32 v62, v62, v100, s77
	v_and_b32_e32 v63, 0xffff0000, v63
	v_and_b32_e32 v78, 0xffff0000, v78
	v_or_b32_sdwa v25, v63, v49 dst_sel:DWORD dst_unused:UNUSED_PAD src0_sel:DWORD src1_sel:WORD_1
	v_or_b32_sdwa v24, v78, v62 dst_sel:DWORD dst_unused:UNUSED_PAD src0_sel:DWORD src1_sel:WORD_1
	v_and_b32_sdwa v203, v51, v120 dst_sel:DWORD dst_unused:UNUSED_PAD src0_sel:WORD_1 src1_sel:DWORD
	global_store_dwordx2 v[112:113], v[24:25], off
	v_mfma_f32_16x16x32_bf16 v[24:27], v[12:15], v[16:19], v[44:47]
	v_and_b32_sdwa v201, v77, v120 dst_sel:DWORD dst_unused:UNUSED_PAD src0_sel:WORD_1 src1_sel:DWORD
	v_and_b32_sdwa v202, v76, v120 dst_sel:DWORD dst_unused:UNUSED_PAD src0_sel:WORD_1 src1_sel:DWORD
	v_add3_u32 v76, v76, v202, s77
	v_and_b32_sdwa v44, v50, v120 dst_sel:DWORD dst_unused:UNUSED_PAD src0_sel:WORD_1 src1_sel:DWORD
	v_mfma_f32_16x16x32_bf16 v[40:43], v[104:107], v[88:91], v[40:43]
	v_add3_u32 v45, v51, v203, s77
	v_add3_u32 v44, v50, v44, s77
	v_add3_u32 v77, v77, v201, s77
	v_mfma_f32_16x16x32_bf16 v[20:23], v[188:191], v[84:87], v[20:23]
; __device__ __forceinline__ unsigned pack2(float a, float b) { return (unsigned)f2bf(a) | ((unsigned)f2bf(b) << 16); }
; __device__ __forceinline__ void xattn_item(const Params& p, char* smem, const int tile, const int hm) {
;     ...
; #pragma unroll
;     for (int m = 0; m < 4; ++m) {
;       const int row = m * 16 + l15;
;       const float inv = 1.f / (sSum[row] + sSum[64 + row] + sSum[128 + row] + sSum[192 + row]);
; #pragma unroll
;       for (int n = 0; n < 4; ++n)
;         *(uint2*)(xo + (size_t)(tok0 + row) * 1024 + hm * 256 + w * 64 + n * 16 + lq * 4) =
;             make_uint2(pack2(acc[m][n][0] * inv, acc[m][n][1] * inv), pack2(acc[m][n][2] * inv, acc[m][n][3] * inv));
;     }
	v_and_b32_e32 v45, 0xffff0000, v45
	v_and_b32_e32 v44, 0xffff0000, v44
	v_or_b32_sdwa v45, v45, v77 dst_sel:DWORD dst_unused:UNUSED_PAD src0_sel:DWORD src1_sel:WORD_1
	v_or_b32_sdwa v44, v44, v76 dst_sel:DWORD dst_unused:UNUSED_PAD src0_sel:DWORD src1_sel:WORD_1
	global_store_dwordx2 v[112:113], v[44:45], off offset:32
	v_mov_b32_e32 v44, v40
	v_mov_b32_e32 v45, v42
	v_mfma_f32_16x16x32_bf16 v[20:23], v[108:111], v[88:91], v[20:23]
	v_mul_f32_e64 v44, v44, v48
	v_mul_f32_e64 v45, v45, v48
	v_mov_b32_e32 v42, v41
	v_pk_mul_f32 v[40:41], v[42:43], v[48:49] op_sel_hi:[1,0]
	v_and_b32_sdwa v42, v45, v120 dst_sel:DWORD dst_unused:UNUSED_PAD src0_sel:WORD_1 src1_sel:DWORD
	v_and_b32_sdwa v43, v44, v120 dst_sel:DWORD dst_unused:UNUSED_PAD src0_sel:WORD_1 src1_sel:DWORD
	v_add3_u32 v43, v44, v43, s77
	v_add3_u32 v42, v45, v42, s77
	v_and_b32_sdwa v44, v41, v120 dst_sel:DWORD dst_unused:UNUSED_PAD src0_sel:WORD_1 src1_sel:DWORD
	v_and_b32_sdwa v45, v40, v120 dst_sel:DWORD dst_unused:UNUSED_PAD src0_sel:WORD_1 src1_sel:DWORD
	v_add3_u32 v41, v41, v44, s77
	v_add3_u32 v40, v40, v45, s77
	v_mov_b32_e32 v44, v20
	v_mov_b32_e32 v45, v22
	v_pk_mul_f32 v[62:63], v[44:45], v[48:49] op_sel_hi:[1,0]
	v_mov_b32_e32 v22, v21
	v_pk_mul_f32 v[20:21], v[22:23], v[48:49] op_sel_hi:[1,0]
	v_and_b32_sdwa v23, v62, v120 dst_sel:DWORD dst_unused:UNUSED_PAD src0_sel:WORD_1 src1_sel:DWORD
	v_add3_u32 v23, v62, v23, s77
	v_and_b32_sdwa v62, v21, v120 dst_sel:DWORD dst_unused:UNUSED_PAD src0_sel:WORD_1 src1_sel:DWORD
	v_and_b32_sdwa v22, v63, v120 dst_sel:DWORD dst_unused:UNUSED_PAD src0_sel:WORD_1 src1_sel:DWORD
	v_add3_u32 v21, v21, v62, s77
	v_add3_u32 v22, v63, v22, s77
	v_and_b32_sdwa v63, v20, v120 dst_sel:DWORD dst_unused:UNUSED_PAD src0_sel:WORD_1 src1_sel:DWORD
	v_and_b32_e32 v21, 0xffff0000, v21
	v_add3_u32 v20, v20, v63, s77
	v_or_b32_sdwa v63, v21, v22 dst_sel:DWORD dst_unused:UNUSED_PAD src0_sel:DWORD src1_sel:WORD_1
	s_waitcnt vmcnt(0) lgkmcnt(0)
	v_add_f32_e32 v21, v128, v129
	s_waitcnt vmcnt(0) lgkmcnt(0)
	v_add_f32_e32 v21, v21, v198
	v_mfma_f32_16x16x32_bf16 v[28:31], v[0:3], v[16:19], v[28:31]
	v_and_b32_e32 v20, 0xffff0000, v20
	v_or_b32_sdwa v62, v20, v23 dst_sel:DWORD dst_unused:UNUSED_PAD src0_sel:DWORD src1_sel:WORD_1
	v_and_b32_e32 v41, 0xffff0000, v41
	v_mfma_f32_16x16x32_bf16 v[44:47], v[0:3], v[68:71], v[140:143]
	v_and_b32_e32 v40, 0xffff0000, v40
	v_or_b32_sdwa v41, v41, v42 dst_sel:DWORD dst_unused:UNUSED_PAD src0_sel:DWORD src1_sel:WORD_1
	v_or_b32_sdwa v40, v40, v43 dst_sel:DWORD dst_unused:UNUSED_PAD src0_sel:DWORD src1_sel:WORD_1
	v_mfma_f32_16x16x32_bf16 v[0:3], v[0:3], v[180:183], v[54:57]
	global_store_dwordx2 v[112:113], v[40:41], off offset:64
	global_store_dwordx2 v[112:113], v[62:63], off offset:96
	s_waitcnt vmcnt(0) lgkmcnt(0)
	v_add_f32_e32 v54, v21, v199
	v_div_scale_f32 v55, s[4:5], v54, v54, 1.0
	v_rcp_f32_e32 v56, v55
	v_mfma_f32_16x16x32_bf16 v[36:39], v[8:11], v[16:19], v[36:39]
	v_mfma_f32_16x16x32_bf16 v[20:23], v[160:163], v[92:95], v[24:27]
	s_nop 2
	v_fma_f32 v24, -v55, v56, 1.0
	v_fmac_f32_e32 v56, v24, v56
	v_mfma_f32_16x16x32_bf16 v[24:27], v[172:175], v[92:95], v[36:39]
	s_nop 2
	v_div_scale_f32 v36, vcc, 1.0, v54, 1.0
	v_mul_f32_e32 v37, v36, v56
	v_fma_f32 v38, -v55, v37, v36
	v_fmac_f32_e32 v37, v38, v56
	v_fma_f32 v36, -v55, v37, v36
	v_div_fmas_f32 v36, v36, v56, v37
	v_div_fixup_f32 v54, v36, v54, 1.0
	v_or_b32_e32 v36, s6, v126
	v_ashrrev_i32_e32 v37, 31, v36
	v_lshlrev_b64 v[56:57], 11, v[36:37]
	v_mfma_f32_16x16x32_bf16 v[36:39], v[164:167], v[96:99], v[20:23]
	v_mfma_f32_16x16x32_bf16 v[48:51], v[4:7], v[68:71], v[168:171]
	s_nop 1
	v_lshl_add_u64 v[20:21], v[52:53], 0, v[56:57]
	s_nop 3
	v_mov_b32_e32 v22, v36
	v_mov_b32_e32 v23, v38
	v_pk_mul_f32 v[22:23], v[22:23], v[54:55] op_sel_hi:[1,0]
	v_mov_b32_e32 v38, v37
	v_pk_mul_f32 v[56:57], v[38:39], v[54:55] op_sel_hi:[1,0]
	v_mfma_f32_16x16x32_bf16 v[36:39], v[184:187], v[148:151], v[44:47]
	v_and_b32_sdwa v55, v23, v120 dst_sel:DWORD dst_unused:UNUSED_PAD src0_sel:WORD_1 src1_sel:DWORD
	v_add3_u32 v23, v23, v55, s77
	s_nop 0
	v_and_b32_sdwa v44, v22, v120 dst_sel:DWORD dst_unused:UNUSED_PAD src0_sel:WORD_1 src1_sel:DWORD
	v_add3_u32 v22, v22, v44, s77
	v_mfma_f32_16x16x32_bf16 v[44:47], v[188:191], v[148:151], v[48:51]
	s_nop 2
	v_and_b32_sdwa v48, v57, v120 dst_sel:DWORD dst_unused:UNUSED_PAD src0_sel:WORD_1 src1_sel:DWORD
	v_and_b32_sdwa v49, v56, v120 dst_sel:DWORD dst_unused:UNUSED_PAD src0_sel:WORD_1 src1_sel:DWORD
	v_add3_u32 v48, v57, v48, s77
	v_add3_u32 v49, v56, v49, s77
	v_and_b32_e32 v48, 0xffff0000, v48
	v_and_b32_e32 v50, 0xffff0000, v49
	v_mfma_f32_16x16x32_bf16 v[16:19], v[4:7], v[16:19], v[32:35]
	v_or_b32_sdwa v49, v48, v23 dst_sel:DWORD dst_unused:UNUSED_PAD src0_sel:DWORD src1_sel:WORD_1
	v_or_b32_sdwa v48, v50, v22 dst_sel:DWORD dst_unused:UNUSED_PAD src0_sel:DWORD src1_sel:WORD_1
	global_store_dwordx2 v[20:21], v[48:49], off
	v_mfma_f32_16x16x32_bf16 v[22:25], v[176:179], v[96:99], v[24:27]
	v_mfma_f32_16x16x32_bf16 v[4:7], v[4:7], v[180:183], v[58:61]
	v_mfma_f32_16x16x32_bf16 v[28:31], v[184:187], v[92:95], v[28:31]
	s_nop 5
	v_mov_b32_e32 v26, v22
	v_mov_b32_e32 v27, v24
	v_pk_mul_f32 v[26:27], v[26:27], v[54:55] op_sel_hi:[1,0]
	v_mfma_f32_16x16x32_bf16 v[32:35], v[12:15], v[68:71], v[80:83]
	v_mov_b32_e32 v24, v23
	v_pk_mul_f32 v[48:49], v[24:25], v[54:55] op_sel_hi:[1,0]
	v_and_b32_sdwa v50, v27, v120 dst_sel:DWORD dst_unused:UNUSED_PAD src0_sel:WORD_1 src1_sel:DWORD
	v_mfma_f32_16x16x32_bf16 v[16:19], v[188:191], v[92:95], v[16:19]
	v_add3_u32 v50, v27, v50, s77
	v_mfma_f32_16x16x32_bf16 v[22:25], v[188:191], v[156:159], v[4:7]
; __device__ __forceinline__ unsigned pack2(float a, float b) { return (unsigned)f2bf(a) | ((unsigned)f2bf(b) << 16); }
; __device__ __forceinline__ void xattn_item(const Params& p, char* smem, const int tile, const int hm) {
;     ...
; #pragma unroll
;     for (int m = 0; m < 4; ++m) {
;       const int row = m * 16 + l15;
;       const float inv = 1.f / (sSum[row] + sSum[64 + row] + sSum[128 + row] + sSum[192 + row]);
; #pragma unroll
;       for (int n = 0; n < 4; ++n)
;         *(uint2*)(xo + (size_t)(tok0 + row) * 1024 + hm * 256 + w * 64 + n * 16 + lq * 4) =
;             make_uint2(pack2(acc[m][n][0] * inv, acc[m][n][1] * inv), pack2(acc[m][n][2] * inv, acc[m][n][3] * inv));
;     }
	s_nop 2
	v_and_b32_sdwa v4, v26, v120 dst_sel:DWORD dst_unused:UNUSED_PAD src0_sel:WORD_1 src1_sel:DWORD
	v_add3_u32 v51, v26, v4, s77
	v_mfma_f32_16x16x32_bf16 v[4:7], v[104:107], v[96:99], v[28:31]
	s_nop 2
	v_and_b32_sdwa v30, v49, v120 dst_sel:DWORD dst_unused:UNUSED_PAD src0_sel:WORD_1 src1_sel:DWORD
	v_and_b32_sdwa v31, v48, v120 dst_sel:DWORD dst_unused:UNUSED_PAD src0_sel:WORD_1 src1_sel:DWORD
	v_mfma_f32_16x16x32_bf16 v[32:35], v[160:163], v[148:151], v[32:35]
	v_mfma_f32_16x16x32_bf16 v[26:29], v[108:111], v[96:99], v[16:19]
	s_nop 2
	v_add3_u32 v16, v49, v30, s77
	v_add3_u32 v17, v48, v31, s77
	v_and_b32_e32 v16, 0xffff0000, v16
	v_and_b32_e32 v18, 0xffff0000, v17
	v_or_b32_sdwa v17, v16, v50 dst_sel:DWORD dst_unused:UNUSED_PAD src0_sel:DWORD src1_sel:WORD_1
	v_or_b32_sdwa v16, v18, v51 dst_sel:DWORD dst_unused:UNUSED_PAD src0_sel:DWORD src1_sel:WORD_1
	global_store_dwordx2 v[20:21], v[16:17], off offset:32
	v_mov_b32_e32 v16, v4
	v_mov_b32_e32 v17, v6
	v_mfma_f32_16x16x32_bf16 v[0:3], v[184:187], v[156:159], v[0:3]
	v_mov_b32_e32 v6, v5
	v_pk_mul_f32 v[4:5], v[6:7], v[54:55] op_sel_hi:[1,0]
	v_mfma_f32_16x16x32_bf16 v[30:33], v[164:167], v[152:155], v[32:35]
	v_mfma_f32_16x16x32_bf16 v[34:37], v[104:107], v[152:155], v[36:39]
	s_nop 2
	v_mul_f32_e64 v38, v16, v54
	v_mul_f32_e64 v39, v17, v54
	v_mfma_f32_16x16x32_bf16 v[16:19], v[108:111], v[152:155], v[44:47]
	v_and_b32_sdwa v6, v39, v120 dst_sel:DWORD dst_unused:UNUSED_PAD src0_sel:WORD_1 src1_sel:DWORD
	v_and_b32_sdwa v7, v38, v120 dst_sel:DWORD dst_unused:UNUSED_PAD src0_sel:WORD_1 src1_sel:DWORD
	v_add3_u32 v38, v38, v7, s77
	v_add3_u32 v39, v39, v6, s77
	v_and_b32_sdwa v6, v5, v120 dst_sel:DWORD dst_unused:UNUSED_PAD src0_sel:WORD_1 src1_sel:DWORD
	v_and_b32_sdwa v7, v4, v120 dst_sel:DWORD dst_unused:UNUSED_PAD src0_sel:WORD_1 src1_sel:DWORD
	v_add3_u32 v5, v5, v6, s77
	v_add3_u32 v44, v4, v7, s77
	v_and_b32_e32 v45, 0xffff0000, v5
	v_mfma_f32_16x16x32_bf16 v[4:7], v[104:107], v[116:119], v[0:3]
	v_or_b32_sdwa v39, v45, v39 dst_sel:DWORD dst_unused:UNUSED_PAD src0_sel:DWORD src1_sel:WORD_1
	s_nop 1
	v_and_b32_e32 v0, 0xffff0000, v44
	v_or_b32_sdwa v38, v0, v38 dst_sel:DWORD dst_unused:UNUSED_PAD src0_sel:DWORD src1_sel:WORD_1
	v_mfma_f32_16x16x32_bf16 v[0:3], v[108:111], v[116:119], v[22:25]
	global_store_dwordx2 v[20:21], v[38:39], off offset:64
	v_lshlrev_b32_e32 v38, 2, v114
	v_or_b32_e32 v39, 0x11800, v38
	v_mov_b32_e32 v22, v26
	v_mov_b32_e32 v23, v28
	v_pk_mul_f32 v[22:23], v[22:23], v[54:55] op_sel_hi:[1,0]
	v_mov_b32_e32 v28, v27
	v_pk_mul_f32 v[24:25], v[28:29], v[54:55] op_sel_hi:[1,0]
	v_and_b32_sdwa v26, v23, v120 dst_sel:DWORD dst_unused:UNUSED_PAD src0_sel:WORD_1 src1_sel:DWORD
	v_and_b32_sdwa v27, v22, v120 dst_sel:DWORD dst_unused:UNUSED_PAD src0_sel:WORD_1 src1_sel:DWORD
	v_add3_u32 v23, v23, v26, s77
	v_and_b32_sdwa v26, v25, v120 dst_sel:DWORD dst_unused:UNUSED_PAD src0_sel:WORD_1 src1_sel:DWORD
	v_add3_u32 v22, v22, v27, s77
	v_and_b32_sdwa v27, v24, v120 dst_sel:DWORD dst_unused:UNUSED_PAD src0_sel:WORD_1 src1_sel:DWORD
	v_add3_u32 v25, v25, v26, s77
	v_lshlrev_b32_e32 v26, 2, v115
	v_add3_u32 v24, v24, v27, s77
	v_or_b32_e32 v27, 0x11800, v26
	v_or_b32_e32 v28, 0x11900, v26
	v_or_b32_e32 v29, 0x11a00, v26
	v_or_b32_e32 v26, 0x11b00, v26
	v_or_b32_e32 v44, 0x11900, v38
	v_or_b32_e32 v45, 0x11a00, v38
	v_or_b32_e32 v38, 0x11b00, v38
	ds_read_b32 v27, v27
	ds_read_b32 v28, v28
	ds_read_b32 v29, v29
	ds_read_b32 v26, v26
	ds_read_b32 v39, v39
	ds_read_b32 v44, v44
	ds_read_b32 v45, v45
	ds_read_b32 v38, v38
	s_waitcnt lgkmcnt(6)
	v_add_f32_e32 v27, v27, v28
	s_waitcnt lgkmcnt(5)
	v_add_f32_e32 v27, v27, v29
	s_waitcnt lgkmcnt(4)
	v_add_f32_e32 v26, v27, v26
	v_div_scale_f32 v27, s[4:5], v26, v26, 1.0
	v_rcp_f32_e32 v28, v27
	v_and_b32_e32 v25, 0xffff0000, v25
	v_and_b32_e32 v24, 0xffff0000, v24
	v_or_b32_sdwa v23, v25, v23 dst_sel:DWORD dst_unused:UNUSED_PAD src0_sel:DWORD src1_sel:WORD_1
	v_or_b32_sdwa v22, v24, v22 dst_sel:DWORD dst_unused:UNUSED_PAD src0_sel:DWORD src1_sel:WORD_1
	global_store_dwordx2 v[20:21], v[22:23], off offset:96
	v_fma_f32 v20, -v27, v28, 1.0
	v_fmac_f32_e32 v28, v20, v28
	v_div_scale_f32 v20, vcc, 1.0, v26, 1.0
	v_mfma_f32_16x16x32_bf16 v[40:43], v[8:11], v[68:71], v[144:147]
	v_mul_f32_e32 v21, v20, v28
	v_fma_f32 v22, -v27, v21, v20
	v_fmac_f32_e32 v21, v22, v28
	v_fma_f32 v20, -v27, v21, v20
	v_mfma_f32_16x16x32_bf16 v[40:43], v[172:175], v[148:151], v[40:43]
	v_div_fmas_f32 v20, v20, v28, v21
	v_div_fixup_f32 v20, v20, v26, 1.0
	v_mov_b32_e32 v24, v30
	v_mov_b32_e32 v25, v32
	v_pk_mul_f32 v[24:25], v[24:25], v[20:21] op_sel_hi:[1,0]
	v_mov_b32_e32 v32, v31
	v_pk_mul_f32 v[26:27], v[32:33], v[20:21] op_sel_hi:[1,0]
	v_and_b32_sdwa v21, v25, v120 dst_sel:DWORD dst_unused:UNUSED_PAD src0_sel:WORD_1 src1_sel:DWORD
	v_and_b32_sdwa v28, v24, v120 dst_sel:DWORD dst_unused:UNUSED_PAD src0_sel:WORD_1 src1_sel:DWORD
	v_mfma_f32_16x16x32_bf16 v[40:43], v[176:179], v[152:155], v[40:43]
	v_or_b32_e32 v22, s6, v115
	v_add3_u32 v24, v24, v28, s77
	v_add3_u32 v21, v25, v21, s77
	v_and_b32_sdwa v25, v27, v120 dst_sel:DWORD dst_unused:UNUSED_PAD src0_sel:WORD_1 src1_sel:DWORD
	v_and_b32_sdwa v28, v26, v120 dst_sel:DWORD dst_unused:UNUSED_PAD src0_sel:WORD_1 src1_sel:DWORD
	v_ashrrev_i32_e32 v23, 31, v22
	v_add3_u32 v25, v27, v25, s77
	v_add3_u32 v26, v26, v28, s77
	v_lshlrev_b64 v[22:23], 11, v[22:23]
	v_and_b32_e32 v25, 0xffff0000, v25
	v_and_b32_e32 v26, 0xffff0000, v26
	v_lshl_add_u64 v[22:23], v[52:53], 0, v[22:23]
	v_or_b32_sdwa v25, v25, v21 dst_sel:DWORD dst_unused:UNUSED_PAD src0_sel:DWORD src1_sel:WORD_1
; __device__ __forceinline__ unsigned pack2(float a, float b) { return (unsigned)f2bf(a) | ((unsigned)f2bf(b) << 16); }
; __device__ __forceinline__ void xattn_item(const Params& p, char* smem, const int tile, const int hm) {
;     ...
; #pragma unroll
;     for (int m = 0; m < 4; ++m) {
;       const int row = m * 16 + l15;
;       const float inv = 1.f / (sSum[row] + sSum[64 + row] + sSum[128 + row] + sSum[192 + row]);
; #pragma unroll
;       for (int n = 0; n < 4; ++n)
;         *(uint2*)(xo + (size_t)(tok0 + row) * 1024 + hm * 256 + w * 64 + n * 16 + lq * 4) =
;             make_uint2(pack2(acc[m][n][0] * inv, acc[m][n][1] * inv), pack2(acc[m][n][2] * inv, acc[m][n][3] * inv));
;     }
	v_or_b32_sdwa v24, v26, v24 dst_sel:DWORD dst_unused:UNUSED_PAD src0_sel:DWORD src1_sel:WORD_1
	global_store_dwordx2 v[22:23], v[24:25], off
	v_mov_b32_e32 v24, v40
	v_mov_b32_e32 v25, v42
	v_pk_mul_f32 v[24:25], v[24:25], v[20:21] op_sel_hi:[1,0]
	v_mov_b32_e32 v42, v41
	v_pk_mul_f32 v[26:27], v[42:43], v[20:21] op_sel_hi:[1,0]
	v_and_b32_sdwa v21, v25, v120 dst_sel:DWORD dst_unused:UNUSED_PAD src0_sel:WORD_1 src1_sel:DWORD
	v_and_b32_sdwa v28, v24, v120 dst_sel:DWORD dst_unused:UNUSED_PAD src0_sel:WORD_1 src1_sel:DWORD
	v_add3_u32 v24, v24, v28, s77
	v_add3_u32 v21, v25, v21, s77
	v_and_b32_sdwa v25, v27, v120 dst_sel:DWORD dst_unused:UNUSED_PAD src0_sel:WORD_1 src1_sel:DWORD
	v_and_b32_sdwa v28, v26, v120 dst_sel:DWORD dst_unused:UNUSED_PAD src0_sel:WORD_1 src1_sel:DWORD
	v_add3_u32 v25, v27, v25, s77
	v_add3_u32 v26, v26, v28, s77
	v_and_b32_e32 v25, 0xffff0000, v25
	v_and_b32_e32 v26, 0xffff0000, v26
	v_or_b32_sdwa v25, v25, v21 dst_sel:DWORD dst_unused:UNUSED_PAD src0_sel:DWORD src1_sel:WORD_1
	v_or_b32_sdwa v24, v26, v24 dst_sel:DWORD dst_unused:UNUSED_PAD src0_sel:DWORD src1_sel:WORD_1
	global_store_dwordx2 v[22:23], v[24:25], off offset:32
	v_mov_b32_e32 v24, v34
	v_mov_b32_e32 v25, v36
	v_pk_mul_f32 v[24:25], v[24:25], v[20:21] op_sel_hi:[1,0]
	v_mov_b32_e32 v36, v35
	v_pk_mul_f32 v[26:27], v[36:37], v[20:21] op_sel_hi:[1,0]
	v_and_b32_sdwa v21, v25, v120 dst_sel:DWORD dst_unused:UNUSED_PAD src0_sel:WORD_1 src1_sel:DWORD
	v_and_b32_sdwa v28, v24, v120 dst_sel:DWORD dst_unused:UNUSED_PAD src0_sel:WORD_1 src1_sel:DWORD
	v_add3_u32 v24, v24, v28, s77
	v_add3_u32 v21, v25, v21, s77
	v_and_b32_sdwa v25, v27, v120 dst_sel:DWORD dst_unused:UNUSED_PAD src0_sel:WORD_1 src1_sel:DWORD
	v_and_b32_sdwa v28, v26, v120 dst_sel:DWORD dst_unused:UNUSED_PAD src0_sel:WORD_1 src1_sel:DWORD
	v_add3_u32 v25, v27, v25, s77
	v_add3_u32 v26, v26, v28, s77
	v_and_b32_e32 v25, 0xffff0000, v25
	v_and_b32_e32 v26, 0xffff0000, v26
	v_or_b32_sdwa v25, v25, v21 dst_sel:DWORD dst_unused:UNUSED_PAD src0_sel:DWORD src1_sel:WORD_1
	v_or_b32_sdwa v24, v26, v24 dst_sel:DWORD dst_unused:UNUSED_PAD src0_sel:DWORD src1_sel:WORD_1
	global_store_dwordx2 v[22:23], v[24:25], off offset:64
	v_mov_b32_e32 v25, v18
	v_mov_b32_e32 v18, v17
	v_mov_b32_e32 v24, v16
	v_pk_mul_f32 v[16:17], v[18:19], v[20:21] op_sel_hi:[1,0]
	v_pk_mul_f32 v[24:25], v[24:25], v[20:21] op_sel_hi:[1,0]
	v_and_b32_sdwa v20, v17, v120 dst_sel:DWORD dst_unused:UNUSED_PAD src0_sel:WORD_1 src1_sel:DWORD
	v_add3_u32 v17, v17, v20, s77
	s_waitcnt lgkmcnt(2)
	v_add_f32_e32 v20, v39, v44
	s_waitcnt lgkmcnt(1)
	v_add_f32_e32 v20, v20, v45
	v_and_b32_sdwa v21, v16, v120 dst_sel:DWORD dst_unused:UNUSED_PAD src0_sel:WORD_1 src1_sel:DWORD
	s_waitcnt lgkmcnt(0)
; __device__ __forceinline__ unsigned pack2(float a, float b) { return (unsigned)f2bf(a) | ((unsigned)f2bf(b) << 16); }
; __device__ __forceinline__ void xattn_item(const Params& p, char* smem, const int tile, const int hm) {
;     ...
; #pragma unroll
;     for (int m = 0; m < 4; ++m) {
;       const int row = m * 16 + l15;
;       const float inv = 1.f / (sSum[row] + sSum[64 + row] + sSum[128 + row] + sSum[192 + row]);
; #pragma unroll
;       for (int n = 0; n < 4; ++n)
;         *(uint2*)(xo + (size_t)(tok0 + row) * 1024 + hm * 256 + w * 64 + n * 16 + lq * 4) =
;             make_uint2(pack2(acc[m][n][0] * inv, acc[m][n][1] * inv), pack2(acc[m][n][2] * inv, acc[m][n][3] * inv));
;     }
	v_add_f32_e32 v20, v20, v38
	v_mfma_f32_16x16x32_bf16 v[12:15], v[12:15], v[180:183], v[72:75]
	v_and_b32_sdwa v19, v24, v120 dst_sel:DWORD dst_unused:UNUSED_PAD src0_sel:WORD_1 src1_sel:DWORD
	v_add3_u32 v16, v16, v21, s77
	v_div_scale_f32 v21, s[4:5], v20, v20, 1.0
	v_add3_u32 v19, v24, v19, s77
	v_rcp_f32_e32 v24, v21
	v_and_b32_sdwa v18, v25, v120 dst_sel:DWORD dst_unused:UNUSED_PAD src0_sel:WORD_1 src1_sel:DWORD
	v_add3_u32 v18, v25, v18, s77
	v_and_b32_e32 v17, 0xffff0000, v17
	v_and_b32_e32 v16, 0xffff0000, v16
	v_mfma_f32_16x16x32_bf16 v[12:15], v[160:163], v[156:159], v[12:15]
	v_or_b32_sdwa v17, v17, v18 dst_sel:DWORD dst_unused:UNUSED_PAD src0_sel:DWORD src1_sel:WORD_1
	v_or_b32_sdwa v16, v16, v19 dst_sel:DWORD dst_unused:UNUSED_PAD src0_sel:DWORD src1_sel:WORD_1
	global_store_dwordx2 v[22:23], v[16:17], off offset:96
	v_fma_f32 v16, -v21, v24, 1.0
	v_fmac_f32_e32 v24, v16, v24
	v_div_scale_f32 v16, vcc, 1.0, v20, 1.0
	v_mfma_f32_16x16x32_bf16 v[8:11], v[8:11], v[180:183], v[64:67]
	v_mul_f32_e32 v17, v16, v24
	v_fma_f32 v18, -v21, v17, v16
	v_fmac_f32_e32 v17, v18, v24
	v_mfma_f32_16x16x32_bf16 v[12:15], v[164:167], v[116:119], v[12:15]
	v_fma_f32 v16, -v21, v17, v16
	v_div_fmas_f32 v16, v16, v24, v17
	v_div_fixup_f32 v16, v16, v20, 1.0
	v_mfma_f32_16x16x32_bf16 v[8:11], v[172:175], v[156:159], v[8:11]
	v_or_b32_e32 v18, s6, v114
	s_nop 2
	v_mov_b32_e32 v20, v12
	v_mov_b32_e32 v21, v14
	v_pk_mul_f32 v[20:21], v[20:21], v[16:17] op_sel_hi:[1,0]
	v_mov_b32_e32 v14, v13
	v_pk_mul_f32 v[12:13], v[14:15], v[16:17] op_sel_hi:[1,0]
	v_and_b32_sdwa v15, v20, v120 dst_sel:DWORD dst_unused:UNUSED_PAD src0_sel:WORD_1 src1_sel:DWORD
	v_mfma_f32_16x16x32_bf16 v[8:11], v[176:179], v[116:119], v[8:11]
	v_add3_u32 v15, v20, v15, s77
	v_and_b32_sdwa v17, v13, v120 dst_sel:DWORD dst_unused:UNUSED_PAD src0_sel:WORD_1 src1_sel:DWORD
	v_and_b32_sdwa v20, v12, v120 dst_sel:DWORD dst_unused:UNUSED_PAD src0_sel:WORD_1 src1_sel:DWORD
	v_ashrrev_i32_e32 v19, 31, v18
	v_and_b32_sdwa v14, v21, v120 dst_sel:DWORD dst_unused:UNUSED_PAD src0_sel:WORD_1 src1_sel:DWORD
	v_add3_u32 v13, v13, v17, s77
	v_add3_u32 v12, v12, v20, s77
	v_lshlrev_b64 v[18:19], 11, v[18:19]
	v_add3_u32 v14, v21, v14, s77
	v_and_b32_e32 v13, 0xffff0000, v13
	v_and_b32_e32 v12, 0xffff0000, v12
	v_lshl_add_u64 v[18:19], v[52:53], 0, v[18:19]
	v_or_b32_sdwa v13, v13, v14 dst_sel:DWORD dst_unused:UNUSED_PAD src0_sel:DWORD src1_sel:WORD_1
	v_or_b32_sdwa v12, v12, v15 dst_sel:DWORD dst_unused:UNUSED_PAD src0_sel:DWORD src1_sel:WORD_1
	global_store_dwordx2 v[18:19], v[12:13], off
	v_mov_b32_e32 v12, v8
	v_mov_b32_e32 v13, v10
	v_pk_mul_f32 v[12:13], v[12:13], v[16:17] op_sel_hi:[1,0]
	v_mov_b32_e32 v10, v9
	v_pk_mul_f32 v[8:9], v[10:11], v[16:17] op_sel_hi:[1,0]
	v_and_b32_sdwa v10, v13, v120 dst_sel:DWORD dst_unused:UNUSED_PAD src0_sel:WORD_1 src1_sel:DWORD
	v_and_b32_sdwa v11, v12, v120 dst_sel:DWORD dst_unused:UNUSED_PAD src0_sel:WORD_1 src1_sel:DWORD
	v_add3_u32 v11, v12, v11, s77
	v_add3_u32 v10, v13, v10, s77
	v_and_b32_sdwa v12, v9, v120 dst_sel:DWORD dst_unused:UNUSED_PAD src0_sel:WORD_1 src1_sel:DWORD
	v_and_b32_sdwa v13, v8, v120 dst_sel:DWORD dst_unused:UNUSED_PAD src0_sel:WORD_1 src1_sel:DWORD
	v_add3_u32 v9, v9, v12, s77
	v_add3_u32 v8, v8, v13, s77
	v_and_b32_e32 v9, 0xffff0000, v9
	v_and_b32_e32 v8, 0xffff0000, v8
	v_or_b32_sdwa v9, v9, v10 dst_sel:DWORD dst_unused:UNUSED_PAD src0_sel:DWORD src1_sel:WORD_1
	v_or_b32_sdwa v8, v8, v11 dst_sel:DWORD dst_unused:UNUSED_PAD src0_sel:DWORD src1_sel:WORD_1
	global_store_dwordx2 v[18:19], v[8:9], off offset:32
	v_mov_b32_e32 v8, v4
	v_mov_b32_e32 v9, v6
	v_pk_mul_f32 v[8:9], v[8:9], v[16:17] op_sel_hi:[1,0]
	v_mov_b32_e32 v6, v5
	v_pk_mul_f32 v[4:5], v[6:7], v[16:17] op_sel_hi:[1,0]
	v_and_b32_sdwa v6, v9, v120 dst_sel:DWORD dst_unused:UNUSED_PAD src0_sel:WORD_1 src1_sel:DWORD
	v_and_b32_sdwa v7, v8, v120 dst_sel:DWORD dst_unused:UNUSED_PAD src0_sel:WORD_1 src1_sel:DWORD
	v_add3_u32 v7, v8, v7, s77
	v_add3_u32 v6, v9, v6, s77
	v_and_b32_sdwa v8, v5, v120 dst_sel:DWORD dst_unused:UNUSED_PAD src0_sel:WORD_1 src1_sel:DWORD
	v_and_b32_sdwa v9, v4, v120 dst_sel:DWORD dst_unused:UNUSED_PAD src0_sel:WORD_1 src1_sel:DWORD
	v_add3_u32 v5, v5, v8, s77
	v_add3_u32 v4, v4, v9, s77
	v_and_b32_e32 v5, 0xffff0000, v5
	v_and_b32_e32 v4, 0xffff0000, v4
	v_or_b32_sdwa v5, v5, v6 dst_sel:DWORD dst_unused:UNUSED_PAD src0_sel:DWORD src1_sel:WORD_1
	v_or_b32_sdwa v4, v4, v7 dst_sel:DWORD dst_unused:UNUSED_PAD src0_sel:DWORD src1_sel:WORD_1
	global_store_dwordx2 v[18:19], v[4:5], off offset:64
	v_mov_b32_e32 v4, v0
	v_mov_b32_e32 v5, v2
	v_pk_mul_f32 v[4:5], v[4:5], v[16:17] op_sel_hi:[1,0]
	v_mov_b32_e32 v2, v1
	v_pk_mul_f32 v[0:1], v[2:3], v[16:17] op_sel_hi:[1,0]
	v_and_b32_sdwa v2, v5, v120 dst_sel:DWORD dst_unused:UNUSED_PAD src0_sel:WORD_1 src1_sel:DWORD
	v_and_b32_sdwa v3, v4, v120 dst_sel:DWORD dst_unused:UNUSED_PAD src0_sel:WORD_1 src1_sel:DWORD
	v_add3_u32 v3, v4, v3, s77
	v_add3_u32 v2, v5, v2, s77
	v_and_b32_sdwa v4, v1, v120 dst_sel:DWORD dst_unused:UNUSED_PAD src0_sel:WORD_1 src1_sel:DWORD
	v_and_b32_sdwa v5, v0, v120 dst_sel:DWORD dst_unused:UNUSED_PAD src0_sel:WORD_1 src1_sel:DWORD
	v_add3_u32 v1, v1, v4, s77
	v_add3_u32 v0, v0, v5, s77
	v_and_b32_e32 v1, 0xffff0000, v1
	v_and_b32_e32 v0, 0xffff0000, v0
	v_or_b32_sdwa v1, v1, v2 dst_sel:DWORD dst_unused:UNUSED_PAD src0_sel:DWORD src1_sel:WORD_1
	v_or_b32_sdwa v0, v0, v3 dst_sel:DWORD dst_unused:UNUSED_PAD src0_sel:DWORD src1_sel:WORD_1
	global_store_dwordx2 v[18:19], v[0:1], off offset:96
